# GEMM MFMA snake order: every adjacent MFMA pair either chains the accumulator or shares an A/B fragment register
# speedup vs baseline: 1.0049x; 1.0018x over previous
; #define PG8_STAGE(bufoff, gbase, voff) do { _Pragma("unroll") for (int _i = 0; _i < 2; ++_i) \
;         __builtin_amdgcn_global_load_lds((const unsigned*)((const char*)(gbase) + (voff)[_i]), (PG8_LAS unsigned*)(lds + (bufoff) + ldsw + _i * 8192), 16, 0, 0); } while (0)
; #define PG8_LDA(dst, b, h) do { _Pragma("unroll") for (int m = 0; m < 4; ++m) _Pragma("unroll") for (int k = 0; k < 2; ++k) dst[m][k] = *(const PG8_LAS bf16x8*)(lds + PG8_SA(b, h) + aoff + m * 2048 + k * 1024); } while (0)
; #define PG8_LDB(dst, b, h) do { _Pragma("unroll") for (int n = 0; n < 2; ++n) _Pragma("unroll") for (int k = 0; k < 2; ++k) dst[n][k] = *(const PG8_LAS bf16x8*)(lds + PG8_SB(b, h) + boff + n * 2048 + k * 1024); } while (0)
; #define PG8_MMA(ai, bj, At, Bt) do { __builtin_amdgcn_s_setprio(1); _Pragma("unroll") for (int m = 0; m < 4; ++m) _Pragma("unroll") for (int n = 0; n < 2; ++n) _Pragma("unroll") for (int k = 0; k < 2; ++k) \
;         acc[ai][bj][m][n] = __builtin_amdgcn_mfma_f32_16x16x32_bf16(Bt[n][k], At[m][k], acc[ai][bj][m][n], 0, 0, 0); __builtin_amdgcn_s_setprio(0); } while (0)
; #define PG8_WAIT_V(n) asm volatile("s_waitcnt vmcnt(" #n ")" ::: "memory")
; #define PG8_WAIT_L(n) asm volatile("s_waitcnt lgkmcnt(" #n ")" ::: "memory")
; #define PG8_BAR __builtin_amdgcn_s_barrier()
; #define PG8_SCHED __builtin_amdgcn_sched_barrier(0)
; template <class Epi, class Sched, bool ALIGN_EPI = false, bool SP2 = false>
; __device__ __forceinline__ void gemm_phase(PG8_LAS unsigned char* lds, const Gemm g, const Sched& S, const Epi& E) {
;     ...
;             const char* a1 = cA + (size_t)(t + 1) * kstep;
;             const char* a2 = last ? nA : cA + (size_t)(t + 2) * kstep; const char* b2 = last ? nB : cB + (size_t)(t + 2) * kstep;
;             const char* a3 = a2 + kstep; const char* b3 = b2 + kstep;
;             if (last && has_next) S.a_ready(nxt);
;             if constexpr (SP2) {
;             PG8_LDB(B0, 0, 0); PG8_LDB(B1, 0, 1); PG8_SCHED; PG8_LDA(At, 0, 0); PG8_STAGE(PG8_SA(1, 1), a1 + hstepA, voffA);
;             PG8_WAIT_V(8); PG8_WAIT_L(0); PG8_BAR; PG8_MMA(0, 0, At, B0); PG8_MMA(0, 1, At, B1); PG8_BAR; PG8_SCHED;
;             PG8_LDA(At, 0, 1); PG8_STAGE(PG8_SB(0, 0), b2, voffB); PG8_STAGE(PG8_SB(0, 1), b2 + hstepB, voffB); PG8_STAGE(PG8_SA(0, 0), a2, voffA);
.LBB0_297:
	s_add_u32 s2, s8, 0xffe00080
	s_addc_u32 s10, s9, -1
	s_add_i32 s33, s17, 0x100
	s_cmpk_eq_i32 vcc_lo, 0x7c
	s_cselect_b32 s61, s49, s10
	s_cselect_b32 s60, s70, s2
	v_add_u32_e32 v144, s33, v147
	s_cselect_b32 s11, s47, s93
	s_cselect_b32 s10, s74, s91
	s_add_i32 s2, s24, 0x100
	ds_read_b128 v[136:139], v144
	ds_read_b128 v[140:143], v144 offset:1024
	ds_read_b128 v[150:153], v144 offset:2048
	ds_read_b128 v[154:157], v144 offset:3072
	v_add_u32_e32 v144, s2, v147
	ds_read_b128 v[158:161], v144
	ds_read_b128 v[162:165], v144 offset:1024
	ds_read_b128 v[166:169], v144 offset:2048
	ds_read_b128 v[170:173], v144 offset:3072
	v_lshl_add_u64 v[144:145], s[8:9], 0, v[132:133]
	s_add_i32 m0, s63, 0xc000
	ds_read_b128 v[174:177], v149
	ds_read_b128 v[178:181], v149 offset:1024
	ds_read_b128 v[182:185], v149 offset:2048
	ds_read_b128 v[186:189], v149 offset:3072
	ds_read_b128 v[190:193], v149 offset:4096
	ds_read_b128 v[210:213], v149 offset:5120
	ds_read_b128 v[222:225], v149 offset:6144
	ds_read_b128 v[228:231], v149 offset:7168
	global_load_lds_dwordx4 v[144:145], off
	v_lshl_add_u64 v[144:145], s[8:9], 0, v[134:135]
	s_add_i32 m0, s63, 0xe000
	s_nop 0
	global_load_lds_dwordx4 v[144:145], off
	s_waitcnt vmcnt(8)
	s_waitcnt lgkmcnt(0)
	s_barrier
	s_setprio 1
	s_waitcnt lgkmcnt(0)
	v_mfma_f32_16x16x32_bf16 v[126:129], v[136:139], v[174:177], v[126:129]
	v_mfma_f32_16x16x32_bf16 v[126:129], v[140:143], v[178:181], v[126:129]
	v_mfma_f32_16x16x32_bf16 v[122:125], v[154:157], v[178:181], v[122:125]
	v_mfma_f32_16x16x32_bf16 v[122:125], v[150:153], v[174:177], v[122:125]
	v_mfma_f32_16x16x32_bf16 v[106:109], v[150:153], v[182:185], v[106:109]
	v_mfma_f32_16x16x32_bf16 v[106:109], v[154:157], v[186:189], v[106:109]
	v_mfma_f32_16x16x32_bf16 v[110:113], v[140:143], v[186:189], v[110:113]
	v_mfma_f32_16x16x32_bf16 v[110:113], v[136:139], v[182:185], v[110:113]
	v_mfma_f32_16x16x32_bf16 v[94:97], v[136:139], v[190:193], v[94:97]
	v_mfma_f32_16x16x32_bf16 v[94:97], v[140:143], v[210:213], v[94:97]
	v_mfma_f32_16x16x32_bf16 v[90:93], v[154:157], v[210:213], v[90:93]
	v_mfma_f32_16x16x32_bf16 v[90:93], v[150:153], v[190:193], v[90:93]
	v_mfma_f32_16x16x32_bf16 v[74:77], v[150:153], v[222:225], v[74:77]
	v_mfma_f32_16x16x32_bf16 v[74:77], v[154:157], v[228:231], v[74:77]
	v_mfma_f32_16x16x32_bf16 v[78:81], v[140:143], v[228:231], v[78:81]
	v_mfma_f32_16x16x32_bf16 v[78:81], v[136:139], v[222:225], v[78:81]
	s_setprio 0
	s_setprio 1
	v_mfma_f32_16x16x32_bf16 v[118:121], v[158:161], v[174:177], v[118:121]
	v_mfma_f32_16x16x32_bf16 v[118:121], v[162:165], v[178:181], v[118:121]
	v_mfma_f32_16x16x32_bf16 v[114:117], v[170:173], v[178:181], v[114:117]
	v_mfma_f32_16x16x32_bf16 v[114:117], v[166:169], v[174:177], v[114:117]
	v_mfma_f32_16x16x32_bf16 v[98:101], v[166:169], v[182:185], v[98:101]
	v_mfma_f32_16x16x32_bf16 v[98:101], v[170:173], v[186:189], v[98:101]
	v_mfma_f32_16x16x32_bf16 v[102:105], v[162:165], v[186:189], v[102:105]
	v_mfma_f32_16x16x32_bf16 v[102:105], v[158:161], v[182:185], v[102:105]
	v_mfma_f32_16x16x32_bf16 v[86:89], v[158:161], v[190:193], v[86:89]
	v_mfma_f32_16x16x32_bf16 v[86:89], v[162:165], v[210:213], v[86:89]
	v_mfma_f32_16x16x32_bf16 v[82:85], v[170:173], v[210:213], v[82:85]
	v_mfma_f32_16x16x32_bf16 v[82:85], v[166:169], v[190:193], v[82:85]
	v_mfma_f32_16x16x32_bf16 v[66:69], v[166:169], v[222:225], v[66:69]
	v_mfma_f32_16x16x32_bf16 v[66:69], v[170:173], v[228:231], v[66:69]
	v_mfma_f32_16x16x32_bf16 v[70:73], v[162:165], v[228:231], v[70:73]
	v_mfma_f32_16x16x32_bf16 v[70:73], v[158:161], v[222:225], v[70:73]
	s_setprio 0
	s_barrier
	s_add_i32 s33, s33, s36
	v_lshl_add_u64 v[144:145], s[10:11], 0, v[0:1]
	s_mov_b32 m0, s33
	ds_read_b128 v[174:177], v149 offset:16384
	ds_read_b128 v[178:181], v149 offset:17408
	ds_read_b128 v[182:185], v149 offset:18432
	ds_read_b128 v[186:189], v149 offset:19456
	ds_read_b128 v[190:193], v149 offset:20480
	ds_read_b128 v[210:213], v149 offset:21504
	ds_read_b128 v[222:225], v149 offset:22528
	ds_read_b128 v[228:231], v149 offset:23552
	global_load_lds_dwordx4 v[144:145], off
	s_add_i32 m0, s33, 0x2000
	s_add_u32 s78, s10, 0x200000
	v_lshl_add_u64 v[194:195], s[10:11], 0, v[130:131]
	s_addc_u32 s79, s11, 0
	s_add_i32 s2, s2, s36
	global_load_lds_dwordx4 v[194:195], off
	v_lshl_add_u64 v[214:215], s[78:79], 0, v[0:1]
	s_mov_b32 m0, s2
	v_lshl_add_u64 v[232:233], s[60:61], 0, v[130:131]
	global_load_lds_dwordx4 v[214:215], off
	v_lshl_add_u64 v[214:215], s[78:79], 0, v[130:131]
	s_add_i32 m0, s2, 0x2000
	s_nop 0
	global_load_lds_dwordx4 v[214:215], off
	v_lshl_add_u64 v[214:215], s[60:61], 0, v[0:1]
	s_mov_b32 m0, s63
	s_nop 0
	global_load_lds_dwordx4 v[214:215], off
	s_mov_b32 m0, s65
	s_nop 0
	global_load_lds_dwordx4 v[232:233], off
	s_waitcnt vmcnt(8)
	s_waitcnt lgkmcnt(0)
	s_barrier
; #define PG8_STAGE(bufoff, gbase, voff) do { _Pragma("unroll") for (int _i = 0; _i < 2; ++_i) \
;         __builtin_amdgcn_global_load_lds((const unsigned*)((const char*)(gbase) + (voff)[_i]), (PG8_LAS unsigned*)(lds + (bufoff) + ldsw + _i * 8192), 16, 0, 0); } while (0)
; #define PG8_LDA(dst, b, h) do { _Pragma("unroll") for (int m = 0; m < 4; ++m) _Pragma("unroll") for (int k = 0; k < 2; ++k) dst[m][k] = *(const PG8_LAS bf16x8*)(lds + PG8_SA(b, h) + aoff + m * 2048 + k * 1024); } while (0)
; #define PG8_LDB(dst, b, h) do { _Pragma("unroll") for (int n = 0; n < 2; ++n) _Pragma("unroll") for (int k = 0; k < 2; ++k) dst[n][k] = *(const PG8_LAS bf16x8*)(lds + PG8_SB(b, h) + boff + n * 2048 + k * 1024); } while (0)
; #define PG8_MMA(ai, bj, At, Bt) do { __builtin_amdgcn_s_setprio(1); _Pragma("unroll") for (int m = 0; m < 4; ++m) _Pragma("unroll") for (int n = 0; n < 2; ++n) _Pragma("unroll") for (int k = 0; k < 2; ++k) \
;         acc[ai][bj][m][n] = __builtin_amdgcn_mfma_f32_16x16x32_bf16(Bt[n][k], At[m][k], acc[ai][bj][m][n], 0, 0, 0); __builtin_amdgcn_s_setprio(0); } while (0)
; #define PG8_WAIT_V(n) asm volatile("s_waitcnt vmcnt(" #n ")" ::: "memory")
; #define PG8_WAIT_L(n) asm volatile("s_waitcnt lgkmcnt(" #n ")" ::: "memory")
; #define PG8_BAR __builtin_amdgcn_s_barrier()
; #define PG8_SCHED __builtin_amdgcn_sched_barrier(0)
; template <class Epi, class Sched, bool ALIGN_EPI = false, bool SP2 = false>
; __device__ __forceinline__ void gemm_phase(PG8_LAS unsigned char* lds, const Gemm g, const Sched& S, const Epi& E) {
;     ...
;             PG8_WAIT_V(8); PG8_WAIT_L(0); PG8_BAR; PG8_MMA(1, 0, At, B0); PG8_MMA(1, 1, At, B1); PG8_BAR; PG8_SCHED;
;             PG8_LDB(B0, 1, 0); PG8_LDB(B1, 1, 1); PG8_SCHED; PG8_LDA(At, 1, 0); PG8_STAGE(PG8_SA(0, 1), a2 + hstepA, voffA);
;             PG8_WAIT_V(8); PG8_WAIT_L(0); PG8_BAR; PG8_MMA(0, 0, At, B0); PG8_MMA(0, 1, At, B1); PG8_BAR; PG8_SCHED;
	s_setprio 1
	s_waitcnt lgkmcnt(0)
	v_mfma_f32_16x16x32_bf16 v[62:65], v[136:139], v[174:177], v[62:65]
	v_mfma_f32_16x16x32_bf16 v[62:65], v[140:143], v[178:181], v[62:65]
	v_mfma_f32_16x16x32_bf16 v[58:61], v[154:157], v[178:181], v[58:61]
	v_mfma_f32_16x16x32_bf16 v[58:61], v[150:153], v[174:177], v[58:61]
	v_mfma_f32_16x16x32_bf16 v[42:45], v[150:153], v[182:185], v[42:45]
	v_mfma_f32_16x16x32_bf16 v[42:45], v[154:157], v[186:189], v[42:45]
	v_mfma_f32_16x16x32_bf16 v[46:49], v[140:143], v[186:189], v[46:49]
	v_mfma_f32_16x16x32_bf16 v[46:49], v[136:139], v[182:185], v[46:49]
	v_mfma_f32_16x16x32_bf16 v[30:33], v[136:139], v[190:193], v[30:33]
	v_mfma_f32_16x16x32_bf16 v[30:33], v[140:143], v[210:213], v[30:33]
	v_mfma_f32_16x16x32_bf16 v[26:29], v[154:157], v[210:213], v[26:29]
	v_mfma_f32_16x16x32_bf16 v[26:29], v[150:153], v[190:193], v[26:29]
	v_mfma_f32_16x16x32_bf16 v[10:13], v[150:153], v[222:225], v[10:13]
	v_mfma_f32_16x16x32_bf16 v[10:13], v[154:157], v[228:231], v[10:13]
	v_mfma_f32_16x16x32_bf16 v[14:17], v[140:143], v[228:231], v[14:17]
	v_mfma_f32_16x16x32_bf16 v[14:17], v[136:139], v[222:225], v[14:17]
	s_setprio 0
	s_setprio 1
	v_mfma_f32_16x16x32_bf16 v[54:57], v[158:161], v[174:177], v[54:57]
	v_mfma_f32_16x16x32_bf16 v[54:57], v[162:165], v[178:181], v[54:57]
	v_mfma_f32_16x16x32_bf16 v[50:53], v[170:173], v[178:181], v[50:53]
	v_mfma_f32_16x16x32_bf16 v[50:53], v[166:169], v[174:177], v[50:53]
	v_mfma_f32_16x16x32_bf16 v[34:37], v[166:169], v[182:185], v[34:37]
	v_mfma_f32_16x16x32_bf16 v[34:37], v[170:173], v[186:189], v[34:37]
	v_mfma_f32_16x16x32_bf16 v[38:41], v[162:165], v[186:189], v[38:41]
	v_mfma_f32_16x16x32_bf16 v[38:41], v[158:161], v[182:185], v[38:41]
	v_mfma_f32_16x16x32_bf16 v[22:25], v[158:161], v[190:193], v[22:25]
	v_mfma_f32_16x16x32_bf16 v[22:25], v[162:165], v[210:213], v[22:25]
	v_mfma_f32_16x16x32_bf16 v[18:21], v[170:173], v[210:213], v[18:21]
	v_mfma_f32_16x16x32_bf16 v[18:21], v[166:169], v[190:193], v[18:21]
	v_mfma_f32_16x16x32_bf16 v[2:5], v[166:169], v[222:225], v[2:5]
	v_mfma_f32_16x16x32_bf16 v[2:5], v[170:173], v[228:231], v[2:5]
	v_mfma_f32_16x16x32_bf16 v[6:9], v[162:165], v[228:231], v[6:9]
	v_mfma_f32_16x16x32_bf16 v[6:9], v[158:161], v[222:225], v[6:9]
	s_setprio 0
	s_barrier
	s_add_i32 s2, s87, 0x100
	s_add_i32 s33, s69, 0x100
	v_add_u32_e32 v154, s2, v147
	v_add_u32_e32 v170, s33, v147
	ds_read_b128 v[136:139], v154
	ds_read_b128 v[140:143], v154 offset:1024
	ds_read_b128 v[150:153], v154 offset:2048
	ds_read_b128 v[154:157], v154 offset:3072
	ds_read_b128 v[158:161], v170
	ds_read_b128 v[162:165], v170 offset:1024
	ds_read_b128 v[166:169], v170 offset:2048
	ds_read_b128 v[170:173], v170 offset:3072
	s_add_u32 s60, s60, 0x200000
	s_addc_u32 s61, s61, 0
	s_mov_b32 m0, s72
	v_lshl_add_u64 v[234:235], s[60:61], 0, v[0:1]
	ds_read_b128 v[174:177], v149 offset:32768
	ds_read_b128 v[178:181], v149 offset:33792
	ds_read_b128 v[182:185], v149 offset:34816
	ds_read_b128 v[186:189], v149 offset:35840
	ds_read_b128 v[190:193], v149 offset:36864
	ds_read_b128 v[210:213], v149 offset:37888
	ds_read_b128 v[222:225], v149 offset:38912
	ds_read_b128 v[228:231], v149 offset:39936
	global_load_lds_dwordx4 v[234:235], off
	v_lshl_add_u64 v[234:235], s[60:61], 0, v[130:131]
	s_mov_b32 m0, s73
	s_nop 0
	global_load_lds_dwordx4 v[234:235], off
	s_waitcnt vmcnt(8)
	s_waitcnt lgkmcnt(0)
	s_barrier
	s_setprio 1
	s_waitcnt lgkmcnt(0)
	v_mfma_f32_16x16x32_bf16 v[126:129], v[136:139], v[174:177], v[126:129]
	v_mfma_f32_16x16x32_bf16 v[126:129], v[140:143], v[178:181], v[126:129]
	v_mfma_f32_16x16x32_bf16 v[122:125], v[154:157], v[178:181], v[122:125]
	v_mfma_f32_16x16x32_bf16 v[122:125], v[150:153], v[174:177], v[122:125]
	v_mfma_f32_16x16x32_bf16 v[106:109], v[150:153], v[182:185], v[106:109]
	v_mfma_f32_16x16x32_bf16 v[106:109], v[154:157], v[186:189], v[106:109]
	v_mfma_f32_16x16x32_bf16 v[110:113], v[140:143], v[186:189], v[110:113]
	v_mfma_f32_16x16x32_bf16 v[110:113], v[136:139], v[182:185], v[110:113]
	v_mfma_f32_16x16x32_bf16 v[94:97], v[136:139], v[190:193], v[94:97]
	v_mfma_f32_16x16x32_bf16 v[94:97], v[140:143], v[210:213], v[94:97]
	v_mfma_f32_16x16x32_bf16 v[90:93], v[154:157], v[210:213], v[90:93]
	v_mfma_f32_16x16x32_bf16 v[90:93], v[150:153], v[190:193], v[90:93]
	v_mfma_f32_16x16x32_bf16 v[74:77], v[150:153], v[222:225], v[74:77]
	v_mfma_f32_16x16x32_bf16 v[74:77], v[154:157], v[228:231], v[74:77]
	v_mfma_f32_16x16x32_bf16 v[78:81], v[140:143], v[228:231], v[78:81]
	v_mfma_f32_16x16x32_bf16 v[78:81], v[136:139], v[222:225], v[78:81]
	s_setprio 0
	s_setprio 1
	v_mfma_f32_16x16x32_bf16 v[118:121], v[158:161], v[174:177], v[118:121]
	v_mfma_f32_16x16x32_bf16 v[118:121], v[162:165], v[178:181], v[118:121]
	v_mfma_f32_16x16x32_bf16 v[114:117], v[170:173], v[178:181], v[114:117]
	v_mfma_f32_16x16x32_bf16 v[114:117], v[166:169], v[174:177], v[114:117]
	v_mfma_f32_16x16x32_bf16 v[98:101], v[166:169], v[182:185], v[98:101]
	v_mfma_f32_16x16x32_bf16 v[98:101], v[170:173], v[186:189], v[98:101]
	v_mfma_f32_16x16x32_bf16 v[102:105], v[162:165], v[186:189], v[102:105]
	v_mfma_f32_16x16x32_bf16 v[102:105], v[158:161], v[182:185], v[102:105]
	v_mfma_f32_16x16x32_bf16 v[86:89], v[158:161], v[190:193], v[86:89]
	v_mfma_f32_16x16x32_bf16 v[86:89], v[162:165], v[210:213], v[86:89]
	v_mfma_f32_16x16x32_bf16 v[82:85], v[170:173], v[210:213], v[82:85]
	v_mfma_f32_16x16x32_bf16 v[82:85], v[166:169], v[190:193], v[82:85]
	v_mfma_f32_16x16x32_bf16 v[66:69], v[166:169], v[222:225], v[66:69]
	v_mfma_f32_16x16x32_bf16 v[66:69], v[170:173], v[228:231], v[66:69]
	v_mfma_f32_16x16x32_bf16 v[70:73], v[162:165], v[228:231], v[70:73]
	v_mfma_f32_16x16x32_bf16 v[70:73], v[158:161], v[222:225], v[70:73]
	s_setprio 0
	s_barrier
; #define PG8_STAGE(bufoff, gbase, voff) do { _Pragma("unroll") for (int _i = 0; _i < 2; ++_i) \
;         __builtin_amdgcn_global_load_lds((const unsigned*)((const char*)(gbase) + (voff)[_i]), (PG8_LAS unsigned*)(lds + (bufoff) + ldsw + _i * 8192), 16, 0, 0); } while (0)
; #define PG8_LDA(dst, b, h) do { _Pragma("unroll") for (int m = 0; m < 4; ++m) _Pragma("unroll") for (int k = 0; k < 2; ++k) dst[m][k] = *(const PG8_LAS bf16x8*)(lds + PG8_SA(b, h) + aoff + m * 2048 + k * 1024); } while (0)
; #define PG8_MMA(ai, bj, At, Bt) do { __builtin_amdgcn_s_setprio(1); _Pragma("unroll") for (int m = 0; m < 4; ++m) _Pragma("unroll") for (int n = 0; n < 2; ++n) _Pragma("unroll") for (int k = 0; k < 2; ++k) \
;         acc[ai][bj][m][n] = __builtin_amdgcn_mfma_f32_16x16x32_bf16(Bt[n][k], At[m][k], acc[ai][bj][m][n], 0, 0, 0); __builtin_amdgcn_s_setprio(0); } while (0)
; #define PG8_WAIT_V(n) asm volatile("s_waitcnt vmcnt(" #n ")" ::: "memory")
; #define PG8_WAIT_L(n) asm volatile("s_waitcnt lgkmcnt(" #n ")" ::: "memory")
; #define PG8_BAR __builtin_amdgcn_s_barrier()
; #define PG8_SCHED __builtin_amdgcn_sched_barrier(0)
; template <class Epi, class Sched, bool ALIGN_EPI = false, bool SP2 = false>
; __device__ __forceinline__ void gemm_phase(PG8_LAS unsigned char* lds, const Gemm g, const Sched& S, const Epi& E) {
;     ...
;             PG8_LDA(At, 1, 1); PG8_STAGE(PG8_SB(1, 0), b3, voffB); PG8_STAGE(PG8_SB(1, 1), b3 + hstepB, voffB); PG8_STAGE(PG8_SA(1, 0), a3, voffA);
;             PG8_WAIT_V(8); PG8_WAIT_L(0); PG8_BAR; PG8_MMA(1, 0, At, B0); PG8_MMA(1, 1, At, B1); PG8_BAR; PG8_SCHED;
;     ...
;         if constexpr (ALIGN_EPI) { if (wr == 0) PG8_BAR; }
	s_add_i32 s2, s2, s36
	v_lshl_add_u64 v[144:145], v[144:145], 0, s[94:95]
	s_mov_b32 m0, s2
	ds_read_b128 v[174:177], v149 offset:49152
	ds_read_b128 v[178:181], v149 offset:50176
	ds_read_b128 v[182:185], v149 offset:51200
	ds_read_b128 v[186:189], v149 offset:52224
	ds_read_b128 v[190:193], v149 offset:53248
	ds_read_b128 v[210:213], v149 offset:54272
	ds_read_b128 v[222:225], v149 offset:55296
	ds_read_b128 v[228:231], v149 offset:56320
	global_load_lds_dwordx4 v[144:145], off
	s_add_i32 m0, s2, 0x2000
	s_add_u32 s10, s10, 0x200080
	v_lshl_add_u64 v[144:145], v[194:195], 0, s[94:95]
	s_addc_u32 s11, s11, 0
	s_add_i32 s2, s33, s36
	global_load_lds_dwordx4 v[144:145], off
	v_lshl_add_u64 v[144:145], s[10:11], 0, v[0:1]
	s_mov_b32 m0, s2
	s_nop 0
	global_load_lds_dwordx4 v[144:145], off
	v_lshl_add_u64 v[144:145], s[10:11], 0, v[130:131]
	s_add_i32 m0, s2, 0x2000
	s_nop 0
	global_load_lds_dwordx4 v[144:145], off
	v_lshl_add_u64 v[144:145], v[214:215], 0, s[94:95]
	s_mov_b32 m0, s76
	s_nop 0
	global_load_lds_dwordx4 v[144:145], off
	v_lshl_add_u64 v[144:145], v[232:233], 0, s[94:95]
	s_mov_b32 m0, s77
	s_nop 0
	global_load_lds_dwordx4 v[144:145], off
	s_waitcnt vmcnt(8)
	s_waitcnt lgkmcnt(0)
	s_barrier
	s_setprio 1
	s_waitcnt lgkmcnt(0)
	v_mfma_f32_16x16x32_bf16 v[62:65], v[136:139], v[174:177], v[62:65]
	v_mfma_f32_16x16x32_bf16 v[62:65], v[140:143], v[178:181], v[62:65]
	v_mfma_f32_16x16x32_bf16 v[58:61], v[154:157], v[178:181], v[58:61]
	v_mfma_f32_16x16x32_bf16 v[58:61], v[150:153], v[174:177], v[58:61]
	v_mfma_f32_16x16x32_bf16 v[42:45], v[150:153], v[182:185], v[42:45]
	v_mfma_f32_16x16x32_bf16 v[42:45], v[154:157], v[186:189], v[42:45]
	v_mfma_f32_16x16x32_bf16 v[46:49], v[140:143], v[186:189], v[46:49]
	v_mfma_f32_16x16x32_bf16 v[46:49], v[136:139], v[182:185], v[46:49]
	v_mfma_f32_16x16x32_bf16 v[30:33], v[136:139], v[190:193], v[30:33]
	v_mfma_f32_16x16x32_bf16 v[30:33], v[140:143], v[210:213], v[30:33]
	v_mfma_f32_16x16x32_bf16 v[26:29], v[154:157], v[210:213], v[26:29]
	v_mfma_f32_16x16x32_bf16 v[26:29], v[150:153], v[190:193], v[26:29]
	v_mfma_f32_16x16x32_bf16 v[10:13], v[150:153], v[222:225], v[10:13]
	v_mfma_f32_16x16x32_bf16 v[10:13], v[154:157], v[228:231], v[10:13]
	v_mfma_f32_16x16x32_bf16 v[14:17], v[140:143], v[228:231], v[14:17]
	v_mfma_f32_16x16x32_bf16 v[14:17], v[136:139], v[222:225], v[14:17]
	s_setprio 0
	s_setprio 1
	v_mfma_f32_16x16x32_bf16 v[54:57], v[158:161], v[174:177], v[54:57]
	v_mfma_f32_16x16x32_bf16 v[54:57], v[162:165], v[178:181], v[54:57]
	v_mfma_f32_16x16x32_bf16 v[50:53], v[170:173], v[178:181], v[50:53]
	v_mfma_f32_16x16x32_bf16 v[50:53], v[166:169], v[174:177], v[50:53]
	v_mfma_f32_16x16x32_bf16 v[34:37], v[166:169], v[182:185], v[34:37]
	v_mfma_f32_16x16x32_bf16 v[34:37], v[170:173], v[186:189], v[34:37]
	v_mfma_f32_16x16x32_bf16 v[38:41], v[162:165], v[186:189], v[38:41]
	v_mfma_f32_16x16x32_bf16 v[38:41], v[158:161], v[182:185], v[38:41]
	v_mfma_f32_16x16x32_bf16 v[22:25], v[158:161], v[190:193], v[22:25]
	v_mfma_f32_16x16x32_bf16 v[22:25], v[162:165], v[210:213], v[22:25]
	v_mfma_f32_16x16x32_bf16 v[18:21], v[170:173], v[210:213], v[18:21]
	v_mfma_f32_16x16x32_bf16 v[18:21], v[166:169], v[190:193], v[18:21]
	v_mfma_f32_16x16x32_bf16 v[2:5], v[166:169], v[222:225], v[2:5]
	v_mfma_f32_16x16x32_bf16 v[2:5], v[170:173], v[228:231], v[2:5]
	v_mfma_f32_16x16x32_bf16 v[6:9], v[162:165], v[228:231], v[6:9]
	v_mfma_f32_16x16x32_bf16 v[6:9], v[158:161], v[222:225], v[6:9]
	s_setprio 0
	s_barrier
	s_add_i32 vcc_lo, vcc_lo, 2
	s_add_u32 s8, s8, 0x100
	s_addc_u32 s9, s9, 0
	s_add_u32 s91, s91, 0x100
	s_addc_u32 s93, s93, 0
	s_cmpk_gt_u32 vcc_lo, 0x7d
	s_cbranch_scc0 .LBB0_297
	s_and_b64 vcc, exec, s[42:43]
	s_cbranch_vccz .LBB0_300
	s_barrier

; #define PG8_STAGE(bufoff, gbase, voff) do { _Pragma("unroll") for (int _i = 0; _i < 2; ++_i) \
;         __builtin_amdgcn_global_load_lds((const unsigned*)((const char*)(gbase) + (voff)[_i]), (PG8_LAS unsigned*)(lds + (bufoff) + ldsw + _i * 8192), 16, 0, 0); } while (0)
; #define PG8_LDA(dst, b, h) do { _Pragma("unroll") for (int m = 0; m < 4; ++m) _Pragma("unroll") for (int k = 0; k < 2; ++k) dst[m][k] = *(const PG8_LAS bf16x8*)(lds + PG8_SA(b, h) + aoff + m * 2048 + k * 1024); } while (0)
; #define PG8_LDB(dst, b, h) do { _Pragma("unroll") for (int n = 0; n < 2; ++n) _Pragma("unroll") for (int k = 0; k < 2; ++k) dst[n][k] = *(const PG8_LAS bf16x8*)(lds + PG8_SB(b, h) + boff + n * 2048 + k * 1024); } while (0)
; #define PG8_MMA(ai, bj, At, Bt) do { __builtin_amdgcn_s_setprio(1); _Pragma("unroll") for (int m = 0; m < 4; ++m) _Pragma("unroll") for (int n = 0; n < 2; ++n) _Pragma("unroll") for (int k = 0; k < 2; ++k) \
;         acc[ai][bj][m][n] = __builtin_amdgcn_mfma_f32_16x16x32_bf16(Bt[n][k], At[m][k], acc[ai][bj][m][n], 0, 0, 0); __builtin_amdgcn_s_setprio(0); } while (0)
; #define PG8_WAIT_V(n) asm volatile("s_waitcnt vmcnt(" #n ")" ::: "memory")
; #define PG8_WAIT_L(n) asm volatile("s_waitcnt lgkmcnt(" #n ")" ::: "memory")
; #define PG8_BAR __builtin_amdgcn_s_barrier()
; #define PG8_SCHED __builtin_amdgcn_sched_barrier(0)
; template <class Epi, class Sched, bool ALIGN_EPI = false, bool SP2 = false>
; __device__ __forceinline__ void gemm_phase(PG8_LAS unsigned char* lds, const Gemm g, const Sched& S, const Epi& E) {
;     ...
;             const char* a1 = cA + (size_t)(t + 1) * kstep;
;             const char* a2 = last ? nA : cA + (size_t)(t + 2) * kstep; const char* b2 = last ? nB : cB + (size_t)(t + 2) * kstep;
;             const char* a3 = a2 + kstep; const char* b3 = b2 + kstep;
;             if (last && has_next) S.a_ready(nxt);
;             if constexpr (SP2) {
;             PG8_LDB(B0, 0, 0); PG8_LDB(B1, 0, 1); PG8_SCHED; PG8_LDA(At, 0, 0); PG8_STAGE(PG8_SA(1, 1), a1 + hstepA, voffA);
;             PG8_WAIT_V(8); PG8_WAIT_L(0); PG8_BAR; PG8_MMA(0, 0, At, B0); PG8_MMA(0, 1, At, B1); PG8_BAR; PG8_SCHED;
;             PG8_LDA(At, 0, 1); PG8_STAGE(PG8_SB(0, 0), b2, voffB); PG8_STAGE(PG8_SB(0, 1), b2 + hstepB, voffB); PG8_STAGE(PG8_SA(0, 0), a2, voffA);
.LBB0_415:
	s_add_u32 s2, s6, 0xfff80080
	s_addc_u32 s33, s7, -1
	s_add_i32 s68, s17, 0x100
	s_cmp_eq_u32 s72, 28
	s_cselect_b32 s47, s39, s33
	s_cselect_b32 s46, s62, s2
	v_add_u32_e32 v144, s68, v147
	s_cselect_b32 s45, s27, s70
	s_cselect_b32 s44, s63, s65
	s_add_i32 s2, s24, 0x100
	ds_read_b128 v[140:143], v144
	ds_read_b128 v[150:153], v144 offset:1024
	ds_read_b128 v[154:157], v144 offset:2048
	ds_read_b128 v[158:161], v144 offset:3072
	v_add_u32_e32 v144, s2, v147
	ds_read_b128 v[162:165], v144
	ds_read_b128 v[166:169], v144 offset:1024
	ds_read_b128 v[170:173], v144 offset:2048
	ds_read_b128 v[174:177], v144 offset:3072
	v_lshl_add_u64 v[194:195], s[6:7], 0, v[136:137]
	s_add_i32 m0, s50, 0xc000
	ds_read_b128 v[178:181], v149
	ds_read_b128 v[182:185], v149 offset:1024
	ds_read_b128 v[186:189], v149 offset:2048
	ds_read_b128 v[190:193], v149 offset:3072
	ds_read_b128 v[210:213], v149 offset:4096
	ds_read_b128 v[222:225], v149 offset:5120
	ds_read_b128 v[228:231], v149 offset:6144
	ds_read_b128 v[232:235], v149 offset:7168
	global_load_lds_dwordx4 v[194:195], off
	v_lshl_add_u64 v[194:195], s[6:7], 0, v[138:139]
	s_add_i32 m0, s50, 0xe000
	s_nop 0
	global_load_lds_dwordx4 v[194:195], off
	s_waitcnt vmcnt(8)
	s_waitcnt lgkmcnt(0)
	s_barrier
	s_setprio 1
	s_waitcnt lgkmcnt(0)
	v_mfma_f32_16x16x32_bf16 v[126:129], v[140:143], v[178:181], v[126:129]
	v_mfma_f32_16x16x32_bf16 v[126:129], v[150:153], v[182:185], v[126:129]
	v_mfma_f32_16x16x32_bf16 v[122:125], v[158:161], v[182:185], v[122:125]
	v_mfma_f32_16x16x32_bf16 v[122:125], v[154:157], v[178:181], v[122:125]
	v_mfma_f32_16x16x32_bf16 v[106:109], v[154:157], v[186:189], v[106:109]
	v_mfma_f32_16x16x32_bf16 v[106:109], v[158:161], v[190:193], v[106:109]
	v_mfma_f32_16x16x32_bf16 v[110:113], v[150:153], v[190:193], v[110:113]
	v_mfma_f32_16x16x32_bf16 v[110:113], v[140:143], v[186:189], v[110:113]
	v_mfma_f32_16x16x32_bf16 v[94:97], v[140:143], v[210:213], v[94:97]
	v_mfma_f32_16x16x32_bf16 v[94:97], v[150:153], v[222:225], v[94:97]
	v_mfma_f32_16x16x32_bf16 v[90:93], v[158:161], v[222:225], v[90:93]
	v_mfma_f32_16x16x32_bf16 v[90:93], v[154:157], v[210:213], v[90:93]
	v_mfma_f32_16x16x32_bf16 v[74:77], v[154:157], v[228:231], v[74:77]
	v_mfma_f32_16x16x32_bf16 v[74:77], v[158:161], v[232:235], v[74:77]
	v_mfma_f32_16x16x32_bf16 v[78:81], v[150:153], v[232:235], v[78:81]
	v_mfma_f32_16x16x32_bf16 v[78:81], v[140:143], v[228:231], v[78:81]
	s_setprio 0
	s_setprio 1
	v_mfma_f32_16x16x32_bf16 v[118:121], v[162:165], v[178:181], v[118:121]
	v_mfma_f32_16x16x32_bf16 v[118:121], v[166:169], v[182:185], v[118:121]
	v_mfma_f32_16x16x32_bf16 v[114:117], v[174:177], v[182:185], v[114:117]
	v_mfma_f32_16x16x32_bf16 v[114:117], v[170:173], v[178:181], v[114:117]
	v_mfma_f32_16x16x32_bf16 v[98:101], v[170:173], v[186:189], v[98:101]
	v_mfma_f32_16x16x32_bf16 v[98:101], v[174:177], v[190:193], v[98:101]
	v_mfma_f32_16x16x32_bf16 v[102:105], v[166:169], v[190:193], v[102:105]
	v_mfma_f32_16x16x32_bf16 v[102:105], v[162:165], v[186:189], v[102:105]
	v_mfma_f32_16x16x32_bf16 v[86:89], v[162:165], v[210:213], v[86:89]
	v_mfma_f32_16x16x32_bf16 v[86:89], v[166:169], v[222:225], v[86:89]
	v_mfma_f32_16x16x32_bf16 v[82:85], v[174:177], v[222:225], v[82:85]
	v_mfma_f32_16x16x32_bf16 v[82:85], v[170:173], v[210:213], v[82:85]
	v_mfma_f32_16x16x32_bf16 v[66:69], v[170:173], v[228:231], v[66:69]
	v_mfma_f32_16x16x32_bf16 v[66:69], v[174:177], v[232:235], v[66:69]
	v_mfma_f32_16x16x32_bf16 v[70:73], v[166:169], v[232:235], v[70:73]
	v_mfma_f32_16x16x32_bf16 v[70:73], v[162:165], v[228:231], v[70:73]
	s_setprio 0
	s_barrier
	s_add_i32 s33, s68, s49
	v_lshl_add_u64 v[194:195], s[44:45], 0, v[0:1]
	s_mov_b32 m0, s33
	ds_read_b128 v[178:181], v149 offset:16384
	ds_read_b128 v[182:185], v149 offset:17408
	ds_read_b128 v[186:189], v149 offset:18432
	ds_read_b128 v[190:193], v149 offset:19456
	ds_read_b128 v[210:213], v149 offset:20480
	ds_read_b128 v[222:225], v149 offset:21504
	ds_read_b128 v[228:231], v149 offset:22528
	ds_read_b128 v[232:235], v149 offset:23552
	global_load_lds_dwordx4 v[194:195], off
	s_add_i32 m0, s33, 0x2000
	s_add_u32 s76, s44, 0x80000
	v_lshl_add_u64 v[214:215], s[44:45], 0, v[130:131]
	s_addc_u32 s77, s45, 0
	s_add_i32 s2, s2, s49
	global_load_lds_dwordx4 v[214:215], off
	v_lshl_add_u64 v[236:237], s[76:77], 0, v[0:1]
	s_mov_b32 m0, s2
	v_lshl_add_u64 v[238:239], s[46:47], 0, v[132:133]
	global_load_lds_dwordx4 v[236:237], off
	v_lshl_add_u64 v[236:237], s[76:77], 0, v[130:131]
	s_add_i32 m0, s2, 0x2000
	s_nop 0
	global_load_lds_dwordx4 v[236:237], off
	v_lshl_add_u64 v[236:237], s[46:47], 0, v[134:135]
	s_mov_b32 m0, s50
	s_nop 0
	global_load_lds_dwordx4 v[236:237], off
	s_mov_b32 m0, s51
	s_nop 0
	global_load_lds_dwordx4 v[238:239], off
	s_waitcnt vmcnt(8)
	s_waitcnt lgkmcnt(0)
	s_barrier
; #define PG8_STAGE(bufoff, gbase, voff) do { _Pragma("unroll") for (int _i = 0; _i < 2; ++_i) \
;         __builtin_amdgcn_global_load_lds((const unsigned*)((const char*)(gbase) + (voff)[_i]), (PG8_LAS unsigned*)(lds + (bufoff) + ldsw + _i * 8192), 16, 0, 0); } while (0)
; #define PG8_LDA(dst, b, h) do { _Pragma("unroll") for (int m = 0; m < 4; ++m) _Pragma("unroll") for (int k = 0; k < 2; ++k) dst[m][k] = *(const PG8_LAS bf16x8*)(lds + PG8_SA(b, h) + aoff + m * 2048 + k * 1024); } while (0)
; #define PG8_LDB(dst, b, h) do { _Pragma("unroll") for (int n = 0; n < 2; ++n) _Pragma("unroll") for (int k = 0; k < 2; ++k) dst[n][k] = *(const PG8_LAS bf16x8*)(lds + PG8_SB(b, h) + boff + n * 2048 + k * 1024); } while (0)
; #define PG8_MMA(ai, bj, At, Bt) do { __builtin_amdgcn_s_setprio(1); _Pragma("unroll") for (int m = 0; m < 4; ++m) _Pragma("unroll") for (int n = 0; n < 2; ++n) _Pragma("unroll") for (int k = 0; k < 2; ++k) \
;         acc[ai][bj][m][n] = __builtin_amdgcn_mfma_f32_16x16x32_bf16(Bt[n][k], At[m][k], acc[ai][bj][m][n], 0, 0, 0); __builtin_amdgcn_s_setprio(0); } while (0)
; #define PG8_WAIT_V(n) asm volatile("s_waitcnt vmcnt(" #n ")" ::: "memory")
; #define PG8_WAIT_L(n) asm volatile("s_waitcnt lgkmcnt(" #n ")" ::: "memory")
; #define PG8_BAR __builtin_amdgcn_s_barrier()
; #define PG8_SCHED __builtin_amdgcn_sched_barrier(0)
; template <class Epi, class Sched, bool ALIGN_EPI = false, bool SP2 = false>
; __device__ __forceinline__ void gemm_phase(PG8_LAS unsigned char* lds, const Gemm g, const Sched& S, const Epi& E) {
;     ...
;             PG8_WAIT_V(8); PG8_WAIT_L(0); PG8_BAR; PG8_MMA(1, 0, At, B0); PG8_MMA(1, 1, At, B1); PG8_BAR; PG8_SCHED;
;             PG8_LDB(B0, 1, 0); PG8_LDB(B1, 1, 1); PG8_SCHED; PG8_LDA(At, 1, 0); PG8_STAGE(PG8_SA(0, 1), a2 + hstepA, voffA);
;             PG8_WAIT_V(8); PG8_WAIT_L(0); PG8_BAR; PG8_MMA(0, 0, At, B0); PG8_MMA(0, 1, At, B1); PG8_BAR; PG8_SCHED;
	s_setprio 1
	s_waitcnt lgkmcnt(0)
	v_mfma_f32_16x16x32_bf16 v[62:65], v[140:143], v[178:181], v[62:65]
	v_mfma_f32_16x16x32_bf16 v[62:65], v[150:153], v[182:185], v[62:65]
	v_mfma_f32_16x16x32_bf16 v[58:61], v[158:161], v[182:185], v[58:61]
	v_mfma_f32_16x16x32_bf16 v[58:61], v[154:157], v[178:181], v[58:61]
	v_mfma_f32_16x16x32_bf16 v[42:45], v[154:157], v[186:189], v[42:45]
	v_mfma_f32_16x16x32_bf16 v[42:45], v[158:161], v[190:193], v[42:45]
	v_mfma_f32_16x16x32_bf16 v[46:49], v[150:153], v[190:193], v[46:49]
	v_mfma_f32_16x16x32_bf16 v[46:49], v[140:143], v[186:189], v[46:49]
	v_mfma_f32_16x16x32_bf16 v[30:33], v[140:143], v[210:213], v[30:33]
	v_mfma_f32_16x16x32_bf16 v[30:33], v[150:153], v[222:225], v[30:33]
	v_mfma_f32_16x16x32_bf16 v[26:29], v[158:161], v[222:225], v[26:29]
	v_mfma_f32_16x16x32_bf16 v[26:29], v[154:157], v[210:213], v[26:29]
	v_mfma_f32_16x16x32_bf16 v[10:13], v[154:157], v[228:231], v[10:13]
	v_mfma_f32_16x16x32_bf16 v[10:13], v[158:161], v[232:235], v[10:13]
	v_mfma_f32_16x16x32_bf16 v[14:17], v[150:153], v[232:235], v[14:17]
	v_mfma_f32_16x16x32_bf16 v[14:17], v[140:143], v[228:231], v[14:17]
	s_setprio 0
	s_setprio 1
	v_mfma_f32_16x16x32_bf16 v[54:57], v[162:165], v[178:181], v[54:57]
	v_mfma_f32_16x16x32_bf16 v[54:57], v[166:169], v[182:185], v[54:57]
	v_mfma_f32_16x16x32_bf16 v[50:53], v[174:177], v[182:185], v[50:53]
	v_mfma_f32_16x16x32_bf16 v[50:53], v[170:173], v[178:181], v[50:53]
	v_mfma_f32_16x16x32_bf16 v[34:37], v[170:173], v[186:189], v[34:37]
	v_mfma_f32_16x16x32_bf16 v[34:37], v[174:177], v[190:193], v[34:37]
	v_mfma_f32_16x16x32_bf16 v[38:41], v[166:169], v[190:193], v[38:41]
	v_mfma_f32_16x16x32_bf16 v[38:41], v[162:165], v[186:189], v[38:41]
	v_mfma_f32_16x16x32_bf16 v[22:25], v[162:165], v[210:213], v[22:25]
	v_mfma_f32_16x16x32_bf16 v[22:25], v[166:169], v[222:225], v[22:25]
	v_mfma_f32_16x16x32_bf16 v[18:21], v[174:177], v[222:225], v[18:21]
	v_mfma_f32_16x16x32_bf16 v[18:21], v[170:173], v[210:213], v[18:21]
	v_mfma_f32_16x16x32_bf16 v[2:5], v[170:173], v[228:231], v[2:5]
	v_mfma_f32_16x16x32_bf16 v[2:5], v[174:177], v[232:235], v[2:5]
	v_mfma_f32_16x16x32_bf16 v[6:9], v[166:169], v[232:235], v[6:9]
	v_mfma_f32_16x16x32_bf16 v[6:9], v[162:165], v[228:231], v[6:9]
	s_setprio 0
	s_barrier
	s_add_i32 s2, s87, 0x100
	v_add_u32_e32 v144, s2, v147
	s_add_i32 s33, s69, 0x100
	ds_read_b128 v[140:143], v144
	ds_read_b128 v[150:153], v144 offset:1024
	ds_read_b128 v[154:157], v144 offset:2048
	ds_read_b128 v[158:161], v144 offset:3072
	v_add_u32_e32 v144, s33, v147
	ds_read_b128 v[162:165], v144
	ds_read_b128 v[166:169], v144 offset:1024
	ds_read_b128 v[170:173], v144 offset:2048
	ds_read_b128 v[174:177], v144 offset:3072
	s_add_u32 s46, s46, 0x80000
	s_addc_u32 s47, s47, 0
	s_mov_b32 m0, s57
	v_lshl_add_u64 v[240:241], s[46:47], 0, v[134:135]
	ds_read_b128 v[178:181], v149 offset:32768
	ds_read_b128 v[182:185], v149 offset:33792
	ds_read_b128 v[186:189], v149 offset:34816
	ds_read_b128 v[190:193], v149 offset:35840
	ds_read_b128 v[210:213], v149 offset:36864
	ds_read_b128 v[222:225], v149 offset:37888
	ds_read_b128 v[228:231], v149 offset:38912
	ds_read_b128 v[232:235], v149 offset:39936
	global_load_lds_dwordx4 v[240:241], off
	v_lshl_add_u64 v[240:241], s[46:47], 0, v[132:133]
	s_mov_b32 m0, s58
	s_nop 0
	global_load_lds_dwordx4 v[240:241], off
	s_waitcnt vmcnt(8)
	s_waitcnt lgkmcnt(0)
	s_barrier
	s_setprio 1
	s_waitcnt lgkmcnt(0)
	v_mfma_f32_16x16x32_bf16 v[126:129], v[140:143], v[178:181], v[126:129]
	v_mfma_f32_16x16x32_bf16 v[126:129], v[150:153], v[182:185], v[126:129]
	v_mfma_f32_16x16x32_bf16 v[122:125], v[158:161], v[182:185], v[122:125]
	v_mfma_f32_16x16x32_bf16 v[122:125], v[154:157], v[178:181], v[122:125]
	v_mfma_f32_16x16x32_bf16 v[106:109], v[154:157], v[186:189], v[106:109]
	v_mfma_f32_16x16x32_bf16 v[106:109], v[158:161], v[190:193], v[106:109]
	v_mfma_f32_16x16x32_bf16 v[110:113], v[150:153], v[190:193], v[110:113]
	v_mfma_f32_16x16x32_bf16 v[110:113], v[140:143], v[186:189], v[110:113]
	v_mfma_f32_16x16x32_bf16 v[94:97], v[140:143], v[210:213], v[94:97]
	v_mfma_f32_16x16x32_bf16 v[94:97], v[150:153], v[222:225], v[94:97]
	v_mfma_f32_16x16x32_bf16 v[90:93], v[158:161], v[222:225], v[90:93]
	v_mfma_f32_16x16x32_bf16 v[90:93], v[154:157], v[210:213], v[90:93]
	v_mfma_f32_16x16x32_bf16 v[74:77], v[154:157], v[228:231], v[74:77]
	v_mfma_f32_16x16x32_bf16 v[74:77], v[158:161], v[232:235], v[74:77]
	v_mfma_f32_16x16x32_bf16 v[78:81], v[150:153], v[232:235], v[78:81]
	v_mfma_f32_16x16x32_bf16 v[78:81], v[140:143], v[228:231], v[78:81]
	s_setprio 0
	s_setprio 1
	v_mfma_f32_16x16x32_bf16 v[118:121], v[162:165], v[178:181], v[118:121]
	v_mfma_f32_16x16x32_bf16 v[118:121], v[166:169], v[182:185], v[118:121]
	v_mfma_f32_16x16x32_bf16 v[114:117], v[174:177], v[182:185], v[114:117]
	v_mfma_f32_16x16x32_bf16 v[114:117], v[170:173], v[178:181], v[114:117]
	v_mfma_f32_16x16x32_bf16 v[98:101], v[170:173], v[186:189], v[98:101]
	v_mfma_f32_16x16x32_bf16 v[98:101], v[174:177], v[190:193], v[98:101]
	v_mfma_f32_16x16x32_bf16 v[102:105], v[166:169], v[190:193], v[102:105]
	v_mfma_f32_16x16x32_bf16 v[102:105], v[162:165], v[186:189], v[102:105]
	v_mfma_f32_16x16x32_bf16 v[86:89], v[162:165], v[210:213], v[86:89]
	v_mfma_f32_16x16x32_bf16 v[86:89], v[166:169], v[222:225], v[86:89]
	v_mfma_f32_16x16x32_bf16 v[82:85], v[174:177], v[222:225], v[82:85]
	v_mfma_f32_16x16x32_bf16 v[82:85], v[170:173], v[210:213], v[82:85]
	v_mfma_f32_16x16x32_bf16 v[66:69], v[170:173], v[228:231], v[66:69]
	v_mfma_f32_16x16x32_bf16 v[66:69], v[174:177], v[232:235], v[66:69]
	v_mfma_f32_16x16x32_bf16 v[70:73], v[166:169], v[232:235], v[70:73]
	v_mfma_f32_16x16x32_bf16 v[70:73], v[162:165], v[228:231], v[70:73]
	s_setprio 0
	s_barrier
; #define PG8_STAGE(bufoff, gbase, voff) do { _Pragma("unroll") for (int _i = 0; _i < 2; ++_i) \
;         __builtin_amdgcn_global_load_lds((const unsigned*)((const char*)(gbase) + (voff)[_i]), (PG8_LAS unsigned*)(lds + (bufoff) + ldsw + _i * 8192), 16, 0, 0); } while (0)
; #define PG8_LDA(dst, b, h) do { _Pragma("unroll") for (int m = 0; m < 4; ++m) _Pragma("unroll") for (int k = 0; k < 2; ++k) dst[m][k] = *(const PG8_LAS bf16x8*)(lds + PG8_SA(b, h) + aoff + m * 2048 + k * 1024); } while (0)
; #define PG8_MMA(ai, bj, At, Bt) do { __builtin_amdgcn_s_setprio(1); _Pragma("unroll") for (int m = 0; m < 4; ++m) _Pragma("unroll") for (int n = 0; n < 2; ++n) _Pragma("unroll") for (int k = 0; k < 2; ++k) \
;         acc[ai][bj][m][n] = __builtin_amdgcn_mfma_f32_16x16x32_bf16(Bt[n][k], At[m][k], acc[ai][bj][m][n], 0, 0, 0); __builtin_amdgcn_s_setprio(0); } while (0)
; #define PG8_WAIT_V(n) asm volatile("s_waitcnt vmcnt(" #n ")" ::: "memory")
; #define PG8_WAIT_L(n) asm volatile("s_waitcnt lgkmcnt(" #n ")" ::: "memory")
; #define PG8_BAR __builtin_amdgcn_s_barrier()
; #define PG8_SCHED __builtin_amdgcn_sched_barrier(0)
; template <class Epi, class Sched, bool ALIGN_EPI = false, bool SP2 = false>
; __device__ __forceinline__ void gemm_phase(PG8_LAS unsigned char* lds, const Gemm g, const Sched& S, const Epi& E) {
;     ...
;             PG8_LDA(At, 1, 1); PG8_STAGE(PG8_SB(1, 0), b3, voffB); PG8_STAGE(PG8_SB(1, 1), b3 + hstepB, voffB); PG8_STAGE(PG8_SA(1, 0), a3, voffA);
;             PG8_WAIT_V(8); PG8_WAIT_L(0); PG8_BAR; PG8_MMA(1, 0, At, B0); PG8_MMA(1, 1, At, B1); PG8_BAR; PG8_SCHED;
;     ...
;         if constexpr (ALIGN_EPI) { if (wr == 0) PG8_BAR; }
	s_add_i32 s2, s2, s49
	v_lshl_add_u64 v[194:195], v[194:195], 0, s[94:95]
	s_mov_b32 m0, s2
	ds_read_b128 v[178:181], v149 offset:49152
	ds_read_b128 v[182:185], v149 offset:50176
	ds_read_b128 v[186:189], v149 offset:51200
	ds_read_b128 v[190:193], v149 offset:52224
	ds_read_b128 v[210:213], v149 offset:53248
	ds_read_b128 v[222:225], v149 offset:54272
	ds_read_b128 v[228:231], v149 offset:55296
	ds_read_b128 v[232:235], v149 offset:56320
	global_load_lds_dwordx4 v[194:195], off
	s_add_i32 m0, s2, 0x2000
	s_add_u32 s44, s44, 0x80080
	v_lshl_add_u64 v[194:195], v[214:215], 0, s[94:95]
	s_addc_u32 s45, s45, 0
	s_add_i32 s2, s33, s49
	global_load_lds_dwordx4 v[194:195], off
	v_lshl_add_u64 v[194:195], s[44:45], 0, v[0:1]
	s_mov_b32 m0, s2
	s_nop 0
	global_load_lds_dwordx4 v[194:195], off
	v_lshl_add_u64 v[194:195], s[44:45], 0, v[130:131]
	s_add_i32 m0, s2, 0x2000
	s_nop 0
	global_load_lds_dwordx4 v[194:195], off
	v_lshl_add_u64 v[194:195], v[236:237], 0, s[94:95]
	s_mov_b32 m0, s59
	s_nop 0
	global_load_lds_dwordx4 v[194:195], off
	v_lshl_add_u64 v[194:195], v[238:239], 0, s[94:95]
	s_mov_b32 m0, s60
	s_nop 0
	global_load_lds_dwordx4 v[194:195], off
	s_waitcnt vmcnt(8)
	s_waitcnt lgkmcnt(0)
	s_barrier
	s_setprio 1
	s_waitcnt lgkmcnt(0)
	v_mfma_f32_16x16x32_bf16 v[62:65], v[140:143], v[178:181], v[62:65]
	v_mfma_f32_16x16x32_bf16 v[62:65], v[150:153], v[182:185], v[62:65]
	v_mfma_f32_16x16x32_bf16 v[58:61], v[158:161], v[182:185], v[58:61]
	v_mfma_f32_16x16x32_bf16 v[58:61], v[154:157], v[178:181], v[58:61]
	v_mfma_f32_16x16x32_bf16 v[42:45], v[154:157], v[186:189], v[42:45]
	v_mfma_f32_16x16x32_bf16 v[42:45], v[158:161], v[190:193], v[42:45]
	v_mfma_f32_16x16x32_bf16 v[46:49], v[150:153], v[190:193], v[46:49]
	v_mfma_f32_16x16x32_bf16 v[46:49], v[140:143], v[186:189], v[46:49]
	v_mfma_f32_16x16x32_bf16 v[30:33], v[140:143], v[210:213], v[30:33]
	v_mfma_f32_16x16x32_bf16 v[30:33], v[150:153], v[222:225], v[30:33]
	v_mfma_f32_16x16x32_bf16 v[26:29], v[158:161], v[222:225], v[26:29]
	v_mfma_f32_16x16x32_bf16 v[26:29], v[154:157], v[210:213], v[26:29]
	v_mfma_f32_16x16x32_bf16 v[10:13], v[154:157], v[228:231], v[10:13]
	v_mfma_f32_16x16x32_bf16 v[10:13], v[158:161], v[232:235], v[10:13]
	v_mfma_f32_16x16x32_bf16 v[14:17], v[150:153], v[232:235], v[14:17]
	v_mfma_f32_16x16x32_bf16 v[14:17], v[140:143], v[228:231], v[14:17]
	s_setprio 0
	s_setprio 1
	v_mfma_f32_16x16x32_bf16 v[54:57], v[162:165], v[178:181], v[54:57]
	v_mfma_f32_16x16x32_bf16 v[54:57], v[166:169], v[182:185], v[54:57]
	v_mfma_f32_16x16x32_bf16 v[50:53], v[174:177], v[182:185], v[50:53]
	v_mfma_f32_16x16x32_bf16 v[50:53], v[170:173], v[178:181], v[50:53]
	v_mfma_f32_16x16x32_bf16 v[34:37], v[170:173], v[186:189], v[34:37]
	v_mfma_f32_16x16x32_bf16 v[34:37], v[174:177], v[190:193], v[34:37]
	v_mfma_f32_16x16x32_bf16 v[38:41], v[166:169], v[190:193], v[38:41]
	v_mfma_f32_16x16x32_bf16 v[38:41], v[162:165], v[186:189], v[38:41]
	v_mfma_f32_16x16x32_bf16 v[22:25], v[162:165], v[210:213], v[22:25]
	v_mfma_f32_16x16x32_bf16 v[22:25], v[166:169], v[222:225], v[22:25]
	v_mfma_f32_16x16x32_bf16 v[18:21], v[174:177], v[222:225], v[18:21]
	v_mfma_f32_16x16x32_bf16 v[18:21], v[170:173], v[210:213], v[18:21]
	v_mfma_f32_16x16x32_bf16 v[2:5], v[170:173], v[228:231], v[2:5]
	v_mfma_f32_16x16x32_bf16 v[2:5], v[174:177], v[232:235], v[2:5]
	v_mfma_f32_16x16x32_bf16 v[6:9], v[166:169], v[232:235], v[6:9]
	v_mfma_f32_16x16x32_bf16 v[6:9], v[162:165], v[228:231], v[6:9]
	s_setprio 0
	s_barrier
	s_add_i32 s72, s72, 2
	s_add_u32 s6, s6, 0x100
	s_addc_u32 s7, s7, 0
	s_add_u32 s65, s65, 0x100
	s_addc_u32 s70, s70, 0
	s_cmp_gt_u32 s72, 29
	s_cbranch_scc0 .LBB0_415
	s_and_b64 vcc, exec, s[14:15]
	s_cbranch_vccz .LBB0_418
	s_barrier

; #define PG8_STAGE(bufoff, gbase, voff) do { _Pragma("unroll") for (int _i = 0; _i < 2; ++_i) \
;         __builtin_amdgcn_global_load_lds((const unsigned*)((const char*)(gbase) + (voff)[_i]), (PG8_LAS unsigned*)(lds + (bufoff) + ldsw + _i * 8192), 16, 0, 0); } while (0)
; #define PG8_LDA(dst, b, h) do { _Pragma("unroll") for (int m = 0; m < 4; ++m) _Pragma("unroll") for (int k = 0; k < 2; ++k) dst[m][k] = *(const PG8_LAS bf16x8*)(lds + PG8_SA(b, h) + aoff + m * 2048 + k * 1024); } while (0)
; #define PG8_LDB(dst, b, h) do { _Pragma("unroll") for (int n = 0; n < 2; ++n) _Pragma("unroll") for (int k = 0; k < 2; ++k) dst[n][k] = *(const PG8_LAS bf16x8*)(lds + PG8_SB(b, h) + boff + n * 2048 + k * 1024); } while (0)
; #define PG8_MMA(ai, bj, At, Bt) do { __builtin_amdgcn_s_setprio(1); _Pragma("unroll") for (int m = 0; m < 4; ++m) _Pragma("unroll") for (int n = 0; n < 2; ++n) _Pragma("unroll") for (int k = 0; k < 2; ++k) \
;         acc[ai][bj][m][n] = __builtin_amdgcn_mfma_f32_16x16x32_bf16(Bt[n][k], At[m][k], acc[ai][bj][m][n], 0, 0, 0); __builtin_amdgcn_s_setprio(0); } while (0)
; #define PG8_WAIT_V(n) asm volatile("s_waitcnt vmcnt(" #n ")" ::: "memory")
; #define PG8_WAIT_L(n) asm volatile("s_waitcnt lgkmcnt(" #n ")" ::: "memory")
; #define PG8_BAR __builtin_amdgcn_s_barrier()
; #define PG8_SCHED __builtin_amdgcn_sched_barrier(0)
; template <class Epi, class Sched, bool ALIGN_EPI = false, bool SP2 = false>
; __device__ __forceinline__ void gemm_phase(PG8_LAS unsigned char* lds, const Gemm g, const Sched& S, const Epi& E) {
;     ...
;             const char* a1 = cA + (size_t)(t + 1) * kstep;
;             const char* a2 = last ? nA : cA + (size_t)(t + 2) * kstep; const char* b2 = last ? nB : cB + (size_t)(t + 2) * kstep;
;             const char* a3 = a2 + kstep; const char* b3 = b2 + kstep;
;             if (last && has_next) S.a_ready(nxt);
;             if constexpr (SP2) {
;             PG8_LDB(B0, 0, 0); PG8_LDB(B1, 0, 1); PG8_SCHED; PG8_LDA(At, 0, 0); PG8_STAGE(PG8_SA(1, 1), a1 + hstepA, voffA);
;             PG8_WAIT_V(8); PG8_WAIT_L(0); PG8_BAR; PG8_MMA(0, 0, At, B0); PG8_MMA(0, 1, At, B1); PG8_BAR; PG8_SCHED;
;             PG8_LDA(At, 0, 1); PG8_STAGE(PG8_SB(0, 0), b2, voffB); PG8_STAGE(PG8_SB(0, 1), b2 + hstepB, voffB); PG8_STAGE(PG8_SA(0, 0), a2, voffA);
.LBB0_456:
	s_add_u32 s2, s8, 0xfff80080
	s_addc_u32 s10, s9, -1
	s_add_i32 s33, s17, 0x100
	s_cmp_eq_u32 s91, 28
	s_cselect_b32 s59, s47, s10
	s_cselect_b32 s58, s57, s2
	v_add_u32_e32 v144, s33, v147
	s_cselect_b32 s11, s45, s83
	s_cselect_b32 s10, s70, s74
	s_add_i32 s2, s24, 0x100
	ds_read_b128 v[136:139], v144
	ds_read_b128 v[140:143], v144 offset:1024
	ds_read_b128 v[150:153], v144 offset:2048
	ds_read_b128 v[154:157], v144 offset:3072
	v_add_u32_e32 v144, s2, v147
	ds_read_b128 v[158:161], v144
	ds_read_b128 v[162:165], v144 offset:1024
	ds_read_b128 v[166:169], v144 offset:2048
	ds_read_b128 v[170:173], v144 offset:3072
	v_lshl_add_u64 v[144:145], s[8:9], 0, v[132:133]
	s_add_i32 m0, s62, 0xc000
	ds_read_b128 v[174:177], v149
	ds_read_b128 v[178:181], v149 offset:1024
	ds_read_b128 v[182:185], v149 offset:2048
	ds_read_b128 v[186:189], v149 offset:3072
	ds_read_b128 v[190:193], v149 offset:4096
	ds_read_b128 v[210:213], v149 offset:5120
	ds_read_b128 v[222:225], v149 offset:6144
	ds_read_b128 v[228:231], v149 offset:7168
	global_load_lds_dwordx4 v[144:145], off
	v_lshl_add_u64 v[144:145], s[8:9], 0, v[134:135]
	s_add_i32 m0, s62, 0xe000
	s_nop 0
	global_load_lds_dwordx4 v[144:145], off
	s_waitcnt vmcnt(8)
	s_waitcnt lgkmcnt(0)
	s_barrier
	s_setprio 1
	s_waitcnt lgkmcnt(0)
	v_mfma_f32_16x16x32_bf16 v[126:129], v[136:139], v[174:177], v[126:129]
	v_mfma_f32_16x16x32_bf16 v[126:129], v[140:143], v[178:181], v[126:129]
	v_mfma_f32_16x16x32_bf16 v[122:125], v[154:157], v[178:181], v[122:125]
	v_mfma_f32_16x16x32_bf16 v[122:125], v[150:153], v[174:177], v[122:125]
	v_mfma_f32_16x16x32_bf16 v[106:109], v[150:153], v[182:185], v[106:109]
	v_mfma_f32_16x16x32_bf16 v[106:109], v[154:157], v[186:189], v[106:109]
	v_mfma_f32_16x16x32_bf16 v[110:113], v[140:143], v[186:189], v[110:113]
	v_mfma_f32_16x16x32_bf16 v[110:113], v[136:139], v[182:185], v[110:113]
	v_mfma_f32_16x16x32_bf16 v[94:97], v[136:139], v[190:193], v[94:97]
	v_mfma_f32_16x16x32_bf16 v[94:97], v[140:143], v[210:213], v[94:97]
	v_mfma_f32_16x16x32_bf16 v[90:93], v[154:157], v[210:213], v[90:93]
	v_mfma_f32_16x16x32_bf16 v[90:93], v[150:153], v[190:193], v[90:93]
	v_mfma_f32_16x16x32_bf16 v[74:77], v[150:153], v[222:225], v[74:77]
	v_mfma_f32_16x16x32_bf16 v[74:77], v[154:157], v[228:231], v[74:77]
	v_mfma_f32_16x16x32_bf16 v[78:81], v[140:143], v[228:231], v[78:81]
	v_mfma_f32_16x16x32_bf16 v[78:81], v[136:139], v[222:225], v[78:81]
	s_setprio 0
	s_setprio 1
	v_mfma_f32_16x16x32_bf16 v[118:121], v[158:161], v[174:177], v[118:121]
	v_mfma_f32_16x16x32_bf16 v[118:121], v[162:165], v[178:181], v[118:121]
	v_mfma_f32_16x16x32_bf16 v[114:117], v[170:173], v[178:181], v[114:117]
	v_mfma_f32_16x16x32_bf16 v[114:117], v[166:169], v[174:177], v[114:117]
	v_mfma_f32_16x16x32_bf16 v[98:101], v[166:169], v[182:185], v[98:101]
	v_mfma_f32_16x16x32_bf16 v[98:101], v[170:173], v[186:189], v[98:101]
	v_mfma_f32_16x16x32_bf16 v[102:105], v[162:165], v[186:189], v[102:105]
	v_mfma_f32_16x16x32_bf16 v[102:105], v[158:161], v[182:185], v[102:105]
	v_mfma_f32_16x16x32_bf16 v[86:89], v[158:161], v[190:193], v[86:89]
	v_mfma_f32_16x16x32_bf16 v[86:89], v[162:165], v[210:213], v[86:89]
	v_mfma_f32_16x16x32_bf16 v[82:85], v[170:173], v[210:213], v[82:85]
	v_mfma_f32_16x16x32_bf16 v[82:85], v[166:169], v[190:193], v[82:85]
	v_mfma_f32_16x16x32_bf16 v[66:69], v[166:169], v[222:225], v[66:69]
	v_mfma_f32_16x16x32_bf16 v[66:69], v[170:173], v[228:231], v[66:69]
	v_mfma_f32_16x16x32_bf16 v[70:73], v[162:165], v[228:231], v[70:73]
	v_mfma_f32_16x16x32_bf16 v[70:73], v[158:161], v[222:225], v[70:73]
	s_setprio 0
	s_barrier
	s_add_i32 s33, s33, s36
	v_lshl_add_u64 v[144:145], s[10:11], 0, v[0:1]
	s_mov_b32 m0, s33
	ds_read_b128 v[174:177], v149 offset:16384
	ds_read_b128 v[178:181], v149 offset:17408
	ds_read_b128 v[182:185], v149 offset:18432
	ds_read_b128 v[186:189], v149 offset:19456
	ds_read_b128 v[190:193], v149 offset:20480
	ds_read_b128 v[210:213], v149 offset:21504
	ds_read_b128 v[222:225], v149 offset:22528
	ds_read_b128 v[228:231], v149 offset:23552
	global_load_lds_dwordx4 v[144:145], off
	s_add_i32 m0, s33, 0x2000
	s_add_u32 s78, s10, 0x80000
	v_lshl_add_u64 v[194:195], s[10:11], 0, v[130:131]
	s_addc_u32 s79, s11, 0
	s_add_i32 s2, s2, s36
	global_load_lds_dwordx4 v[194:195], off
	v_lshl_add_u64 v[214:215], s[78:79], 0, v[0:1]
	s_mov_b32 m0, s2
	v_lshl_add_u64 v[232:233], s[58:59], 0, v[130:131]
	global_load_lds_dwordx4 v[214:215], off
	v_lshl_add_u64 v[214:215], s[78:79], 0, v[130:131]
	s_add_i32 m0, s2, 0x2000
	s_nop 0
	global_load_lds_dwordx4 v[214:215], off
	v_lshl_add_u64 v[214:215], s[58:59], 0, v[0:1]
	s_mov_b32 m0, s62
	s_nop 0
	global_load_lds_dwordx4 v[214:215], off
	s_mov_b32 m0, s63
	s_nop 0
	global_load_lds_dwordx4 v[232:233], off
	s_waitcnt vmcnt(8)
	s_waitcnt lgkmcnt(0)
	s_barrier
; #define PG8_STAGE(bufoff, gbase, voff) do { _Pragma("unroll") for (int _i = 0; _i < 2; ++_i) \
;         __builtin_amdgcn_global_load_lds((const unsigned*)((const char*)(gbase) + (voff)[_i]), (PG8_LAS unsigned*)(lds + (bufoff) + ldsw + _i * 8192), 16, 0, 0); } while (0)
; #define PG8_LDA(dst, b, h) do { _Pragma("unroll") for (int m = 0; m < 4; ++m) _Pragma("unroll") for (int k = 0; k < 2; ++k) dst[m][k] = *(const PG8_LAS bf16x8*)(lds + PG8_SA(b, h) + aoff + m * 2048 + k * 1024); } while (0)
; #define PG8_LDB(dst, b, h) do { _Pragma("unroll") for (int n = 0; n < 2; ++n) _Pragma("unroll") for (int k = 0; k < 2; ++k) dst[n][k] = *(const PG8_LAS bf16x8*)(lds + PG8_SB(b, h) + boff + n * 2048 + k * 1024); } while (0)
; #define PG8_MMA(ai, bj, At, Bt) do { __builtin_amdgcn_s_setprio(1); _Pragma("unroll") for (int m = 0; m < 4; ++m) _Pragma("unroll") for (int n = 0; n < 2; ++n) _Pragma("unroll") for (int k = 0; k < 2; ++k) \
;         acc[ai][bj][m][n] = __builtin_amdgcn_mfma_f32_16x16x32_bf16(Bt[n][k], At[m][k], acc[ai][bj][m][n], 0, 0, 0); __builtin_amdgcn_s_setprio(0); } while (0)
; #define PG8_WAIT_V(n) asm volatile("s_waitcnt vmcnt(" #n ")" ::: "memory")
; #define PG8_WAIT_L(n) asm volatile("s_waitcnt lgkmcnt(" #n ")" ::: "memory")
; #define PG8_BAR __builtin_amdgcn_s_barrier()
; #define PG8_SCHED __builtin_amdgcn_sched_barrier(0)
; template <class Epi, class Sched, bool ALIGN_EPI = false, bool SP2 = false>
; __device__ __forceinline__ void gemm_phase(PG8_LAS unsigned char* lds, const Gemm g, const Sched& S, const Epi& E) {
;     ...
;             PG8_WAIT_V(8); PG8_WAIT_L(0); PG8_BAR; PG8_MMA(1, 0, At, B0); PG8_MMA(1, 1, At, B1); PG8_BAR; PG8_SCHED;
;             PG8_LDB(B0, 1, 0); PG8_LDB(B1, 1, 1); PG8_SCHED; PG8_LDA(At, 1, 0); PG8_STAGE(PG8_SA(0, 1), a2 + hstepA, voffA);
;             PG8_WAIT_V(8); PG8_WAIT_L(0); PG8_BAR; PG8_MMA(0, 0, At, B0); PG8_MMA(0, 1, At, B1); PG8_BAR; PG8_SCHED;
	s_setprio 1
	s_waitcnt lgkmcnt(0)
	v_mfma_f32_16x16x32_bf16 v[62:65], v[136:139], v[174:177], v[62:65]
	v_mfma_f32_16x16x32_bf16 v[62:65], v[140:143], v[178:181], v[62:65]
	v_mfma_f32_16x16x32_bf16 v[58:61], v[154:157], v[178:181], v[58:61]
	v_mfma_f32_16x16x32_bf16 v[58:61], v[150:153], v[174:177], v[58:61]
	v_mfma_f32_16x16x32_bf16 v[42:45], v[150:153], v[182:185], v[42:45]
	v_mfma_f32_16x16x32_bf16 v[42:45], v[154:157], v[186:189], v[42:45]
	v_mfma_f32_16x16x32_bf16 v[46:49], v[140:143], v[186:189], v[46:49]
	v_mfma_f32_16x16x32_bf16 v[46:49], v[136:139], v[182:185], v[46:49]
	v_mfma_f32_16x16x32_bf16 v[30:33], v[136:139], v[190:193], v[30:33]
	v_mfma_f32_16x16x32_bf16 v[30:33], v[140:143], v[210:213], v[30:33]
	v_mfma_f32_16x16x32_bf16 v[26:29], v[154:157], v[210:213], v[26:29]
	v_mfma_f32_16x16x32_bf16 v[26:29], v[150:153], v[190:193], v[26:29]
	v_mfma_f32_16x16x32_bf16 v[10:13], v[150:153], v[222:225], v[10:13]
	v_mfma_f32_16x16x32_bf16 v[10:13], v[154:157], v[228:231], v[10:13]
	v_mfma_f32_16x16x32_bf16 v[14:17], v[140:143], v[228:231], v[14:17]
	v_mfma_f32_16x16x32_bf16 v[14:17], v[136:139], v[222:225], v[14:17]
	s_setprio 0
	s_setprio 1
	v_mfma_f32_16x16x32_bf16 v[54:57], v[158:161], v[174:177], v[54:57]
	v_mfma_f32_16x16x32_bf16 v[54:57], v[162:165], v[178:181], v[54:57]
	v_mfma_f32_16x16x32_bf16 v[50:53], v[170:173], v[178:181], v[50:53]
	v_mfma_f32_16x16x32_bf16 v[50:53], v[166:169], v[174:177], v[50:53]
	v_mfma_f32_16x16x32_bf16 v[34:37], v[166:169], v[182:185], v[34:37]
	v_mfma_f32_16x16x32_bf16 v[34:37], v[170:173], v[186:189], v[34:37]
	v_mfma_f32_16x16x32_bf16 v[38:41], v[162:165], v[186:189], v[38:41]
	v_mfma_f32_16x16x32_bf16 v[38:41], v[158:161], v[182:185], v[38:41]
	v_mfma_f32_16x16x32_bf16 v[22:25], v[158:161], v[190:193], v[22:25]
	v_mfma_f32_16x16x32_bf16 v[22:25], v[162:165], v[210:213], v[22:25]
	v_mfma_f32_16x16x32_bf16 v[18:21], v[170:173], v[210:213], v[18:21]
	v_mfma_f32_16x16x32_bf16 v[18:21], v[166:169], v[190:193], v[18:21]
	v_mfma_f32_16x16x32_bf16 v[2:5], v[166:169], v[222:225], v[2:5]
	v_mfma_f32_16x16x32_bf16 v[2:5], v[170:173], v[228:231], v[2:5]
	v_mfma_f32_16x16x32_bf16 v[6:9], v[162:165], v[228:231], v[6:9]
	v_mfma_f32_16x16x32_bf16 v[6:9], v[158:161], v[222:225], v[6:9]
	s_setprio 0
	s_barrier
	s_add_i32 s2, s87, 0x100
	s_add_i32 s33, s69, 0x100
	v_add_u32_e32 v154, s2, v147
	v_add_u32_e32 v170, s33, v147
	ds_read_b128 v[136:139], v154
	ds_read_b128 v[140:143], v154 offset:1024
	ds_read_b128 v[150:153], v154 offset:2048
	ds_read_b128 v[154:157], v154 offset:3072
	ds_read_b128 v[158:161], v170
	ds_read_b128 v[162:165], v170 offset:1024
	ds_read_b128 v[166:169], v170 offset:2048
	ds_read_b128 v[170:173], v170 offset:3072
	s_add_u32 s58, s58, 0x80000
	s_addc_u32 s59, s59, 0
	s_mov_b32 m0, s65
	v_lshl_add_u64 v[234:235], s[58:59], 0, v[0:1]
	ds_read_b128 v[174:177], v149 offset:32768
	ds_read_b128 v[178:181], v149 offset:33792
	ds_read_b128 v[182:185], v149 offset:34816
	ds_read_b128 v[186:189], v149 offset:35840
	ds_read_b128 v[190:193], v149 offset:36864
	ds_read_b128 v[210:213], v149 offset:37888
	ds_read_b128 v[222:225], v149 offset:38912
	ds_read_b128 v[228:231], v149 offset:39936
	global_load_lds_dwordx4 v[234:235], off
	v_lshl_add_u64 v[234:235], s[58:59], 0, v[130:131]
	s_mov_b32 m0, s72
	s_nop 0
	global_load_lds_dwordx4 v[234:235], off
	s_waitcnt vmcnt(8)
	s_waitcnt lgkmcnt(0)
	s_barrier
	s_setprio 1
	s_waitcnt lgkmcnt(0)
	v_mfma_f32_16x16x32_bf16 v[126:129], v[136:139], v[174:177], v[126:129]
	v_mfma_f32_16x16x32_bf16 v[126:129], v[140:143], v[178:181], v[126:129]
	v_mfma_f32_16x16x32_bf16 v[122:125], v[154:157], v[178:181], v[122:125]
	v_mfma_f32_16x16x32_bf16 v[122:125], v[150:153], v[174:177], v[122:125]
	v_mfma_f32_16x16x32_bf16 v[106:109], v[150:153], v[182:185], v[106:109]
	v_mfma_f32_16x16x32_bf16 v[106:109], v[154:157], v[186:189], v[106:109]
	v_mfma_f32_16x16x32_bf16 v[110:113], v[140:143], v[186:189], v[110:113]
	v_mfma_f32_16x16x32_bf16 v[110:113], v[136:139], v[182:185], v[110:113]
	v_mfma_f32_16x16x32_bf16 v[94:97], v[136:139], v[190:193], v[94:97]
	v_mfma_f32_16x16x32_bf16 v[94:97], v[140:143], v[210:213], v[94:97]
	v_mfma_f32_16x16x32_bf16 v[90:93], v[154:157], v[210:213], v[90:93]
	v_mfma_f32_16x16x32_bf16 v[90:93], v[150:153], v[190:193], v[90:93]
	v_mfma_f32_16x16x32_bf16 v[74:77], v[150:153], v[222:225], v[74:77]
	v_mfma_f32_16x16x32_bf16 v[74:77], v[154:157], v[228:231], v[74:77]
	v_mfma_f32_16x16x32_bf16 v[78:81], v[140:143], v[228:231], v[78:81]
	v_mfma_f32_16x16x32_bf16 v[78:81], v[136:139], v[222:225], v[78:81]
	s_setprio 0
	s_setprio 1
	v_mfma_f32_16x16x32_bf16 v[118:121], v[158:161], v[174:177], v[118:121]
	v_mfma_f32_16x16x32_bf16 v[118:121], v[162:165], v[178:181], v[118:121]
	v_mfma_f32_16x16x32_bf16 v[114:117], v[170:173], v[178:181], v[114:117]
	v_mfma_f32_16x16x32_bf16 v[114:117], v[166:169], v[174:177], v[114:117]
	v_mfma_f32_16x16x32_bf16 v[98:101], v[166:169], v[182:185], v[98:101]
	v_mfma_f32_16x16x32_bf16 v[98:101], v[170:173], v[186:189], v[98:101]
	v_mfma_f32_16x16x32_bf16 v[102:105], v[162:165], v[186:189], v[102:105]
	v_mfma_f32_16x16x32_bf16 v[102:105], v[158:161], v[182:185], v[102:105]
	v_mfma_f32_16x16x32_bf16 v[86:89], v[158:161], v[190:193], v[86:89]
	v_mfma_f32_16x16x32_bf16 v[86:89], v[162:165], v[210:213], v[86:89]
	v_mfma_f32_16x16x32_bf16 v[82:85], v[170:173], v[210:213], v[82:85]
	v_mfma_f32_16x16x32_bf16 v[82:85], v[166:169], v[190:193], v[82:85]
	v_mfma_f32_16x16x32_bf16 v[66:69], v[166:169], v[222:225], v[66:69]
	v_mfma_f32_16x16x32_bf16 v[66:69], v[170:173], v[228:231], v[66:69]
	v_mfma_f32_16x16x32_bf16 v[70:73], v[162:165], v[228:231], v[70:73]
	v_mfma_f32_16x16x32_bf16 v[70:73], v[158:161], v[222:225], v[70:73]
	s_setprio 0
	s_barrier
; #define PG8_STAGE(bufoff, gbase, voff) do { _Pragma("unroll") for (int _i = 0; _i < 2; ++_i) \
;         __builtin_amdgcn_global_load_lds((const unsigned*)((const char*)(gbase) + (voff)[_i]), (PG8_LAS unsigned*)(lds + (bufoff) + ldsw + _i * 8192), 16, 0, 0); } while (0)
; #define PG8_LDA(dst, b, h) do { _Pragma("unroll") for (int m = 0; m < 4; ++m) _Pragma("unroll") for (int k = 0; k < 2; ++k) dst[m][k] = *(const PG8_LAS bf16x8*)(lds + PG8_SA(b, h) + aoff + m * 2048 + k * 1024); } while (0)
; #define PG8_MMA(ai, bj, At, Bt) do { __builtin_amdgcn_s_setprio(1); _Pragma("unroll") for (int m = 0; m < 4; ++m) _Pragma("unroll") for (int n = 0; n < 2; ++n) _Pragma("unroll") for (int k = 0; k < 2; ++k) \
;         acc[ai][bj][m][n] = __builtin_amdgcn_mfma_f32_16x16x32_bf16(Bt[n][k], At[m][k], acc[ai][bj][m][n], 0, 0, 0); __builtin_amdgcn_s_setprio(0); } while (0)
; #define PG8_WAIT_V(n) asm volatile("s_waitcnt vmcnt(" #n ")" ::: "memory")
; #define PG8_WAIT_L(n) asm volatile("s_waitcnt lgkmcnt(" #n ")" ::: "memory")
; #define PG8_BAR __builtin_amdgcn_s_barrier()
; #define PG8_SCHED __builtin_amdgcn_sched_barrier(0)
; template <class Epi, class Sched, bool ALIGN_EPI = false, bool SP2 = false>
; __device__ __forceinline__ void gemm_phase(PG8_LAS unsigned char* lds, const Gemm g, const Sched& S, const Epi& E) {
;     ...
;             PG8_LDA(At, 1, 1); PG8_STAGE(PG8_SB(1, 0), b3, voffB); PG8_STAGE(PG8_SB(1, 1), b3 + hstepB, voffB); PG8_STAGE(PG8_SA(1, 0), a3, voffA);
;             PG8_WAIT_V(8); PG8_WAIT_L(0); PG8_BAR; PG8_MMA(1, 0, At, B0); PG8_MMA(1, 1, At, B1); PG8_BAR; PG8_SCHED;
;     ...
;         if constexpr (ALIGN_EPI) { if (wr == 0) PG8_BAR; }
	s_add_i32 s2, s2, s36
	v_lshl_add_u64 v[144:145], v[144:145], 0, s[94:95]
	s_mov_b32 m0, s2
	ds_read_b128 v[174:177], v149 offset:49152
	ds_read_b128 v[178:181], v149 offset:50176
	ds_read_b128 v[182:185], v149 offset:51200
	ds_read_b128 v[186:189], v149 offset:52224
	ds_read_b128 v[190:193], v149 offset:53248
	ds_read_b128 v[210:213], v149 offset:54272
	ds_read_b128 v[222:225], v149 offset:55296
	ds_read_b128 v[228:231], v149 offset:56320
	global_load_lds_dwordx4 v[144:145], off
	s_add_i32 m0, s2, 0x2000
	s_add_u32 s10, s10, 0x80080
	v_lshl_add_u64 v[144:145], v[194:195], 0, s[94:95]
	s_addc_u32 s11, s11, 0
	s_add_i32 s2, s33, s36
	global_load_lds_dwordx4 v[144:145], off
	v_lshl_add_u64 v[144:145], s[10:11], 0, v[0:1]
	s_mov_b32 m0, s2
	s_nop 0
	global_load_lds_dwordx4 v[144:145], off
	v_lshl_add_u64 v[144:145], s[10:11], 0, v[130:131]
	s_add_i32 m0, s2, 0x2000
	s_nop 0
	global_load_lds_dwordx4 v[144:145], off
	v_lshl_add_u64 v[144:145], v[214:215], 0, s[94:95]
	s_mov_b32 m0, s73
	s_nop 0
	global_load_lds_dwordx4 v[144:145], off
	v_lshl_add_u64 v[144:145], v[232:233], 0, s[94:95]
	s_mov_b32 m0, s76
	s_nop 0
	global_load_lds_dwordx4 v[144:145], off
	s_waitcnt vmcnt(8)
	s_waitcnt lgkmcnt(0)
	s_barrier
	s_setprio 1
	s_waitcnt lgkmcnt(0)
	v_mfma_f32_16x16x32_bf16 v[62:65], v[136:139], v[174:177], v[62:65]
	v_mfma_f32_16x16x32_bf16 v[62:65], v[140:143], v[178:181], v[62:65]
	v_mfma_f32_16x16x32_bf16 v[58:61], v[154:157], v[178:181], v[58:61]
	v_mfma_f32_16x16x32_bf16 v[58:61], v[150:153], v[174:177], v[58:61]
	v_mfma_f32_16x16x32_bf16 v[42:45], v[150:153], v[182:185], v[42:45]
	v_mfma_f32_16x16x32_bf16 v[42:45], v[154:157], v[186:189], v[42:45]
	v_mfma_f32_16x16x32_bf16 v[46:49], v[140:143], v[186:189], v[46:49]
	v_mfma_f32_16x16x32_bf16 v[46:49], v[136:139], v[182:185], v[46:49]
	v_mfma_f32_16x16x32_bf16 v[30:33], v[136:139], v[190:193], v[30:33]
	v_mfma_f32_16x16x32_bf16 v[30:33], v[140:143], v[210:213], v[30:33]
	v_mfma_f32_16x16x32_bf16 v[26:29], v[154:157], v[210:213], v[26:29]
	v_mfma_f32_16x16x32_bf16 v[26:29], v[150:153], v[190:193], v[26:29]
	v_mfma_f32_16x16x32_bf16 v[10:13], v[150:153], v[222:225], v[10:13]
	v_mfma_f32_16x16x32_bf16 v[10:13], v[154:157], v[228:231], v[10:13]
	v_mfma_f32_16x16x32_bf16 v[14:17], v[140:143], v[228:231], v[14:17]
	v_mfma_f32_16x16x32_bf16 v[14:17], v[136:139], v[222:225], v[14:17]
	s_setprio 0
	s_setprio 1
	v_mfma_f32_16x16x32_bf16 v[54:57], v[158:161], v[174:177], v[54:57]
	v_mfma_f32_16x16x32_bf16 v[54:57], v[162:165], v[178:181], v[54:57]
	v_mfma_f32_16x16x32_bf16 v[50:53], v[170:173], v[178:181], v[50:53]
	v_mfma_f32_16x16x32_bf16 v[50:53], v[166:169], v[174:177], v[50:53]
	v_mfma_f32_16x16x32_bf16 v[34:37], v[166:169], v[182:185], v[34:37]
	v_mfma_f32_16x16x32_bf16 v[34:37], v[170:173], v[186:189], v[34:37]
	v_mfma_f32_16x16x32_bf16 v[38:41], v[162:165], v[186:189], v[38:41]
	v_mfma_f32_16x16x32_bf16 v[38:41], v[158:161], v[182:185], v[38:41]
	v_mfma_f32_16x16x32_bf16 v[22:25], v[158:161], v[190:193], v[22:25]
	v_mfma_f32_16x16x32_bf16 v[22:25], v[162:165], v[210:213], v[22:25]
	v_mfma_f32_16x16x32_bf16 v[18:21], v[170:173], v[210:213], v[18:21]
	v_mfma_f32_16x16x32_bf16 v[18:21], v[166:169], v[190:193], v[18:21]
	v_mfma_f32_16x16x32_bf16 v[2:5], v[166:169], v[222:225], v[2:5]
	v_mfma_f32_16x16x32_bf16 v[2:5], v[170:173], v[228:231], v[2:5]
	v_mfma_f32_16x16x32_bf16 v[6:9], v[162:165], v[228:231], v[6:9]
	v_mfma_f32_16x16x32_bf16 v[6:9], v[158:161], v[222:225], v[6:9]
	s_setprio 0
	s_barrier
	s_add_i32 s91, s91, 2
	s_add_u32 s8, s8, 0x100
	s_addc_u32 s9, s9, 0
	s_add_u32 s74, s74, 0x100
	s_addc_u32 s83, s83, 0
	s_cmp_gt_u32 s91, 29
	s_cbranch_scc0 .LBB0_456
	s_and_b64 vcc, exec, s[38:39]
	s_cbranch_vccz .LBB0_459
	s_barrier

; #define PG8_STAGE(bufoff, gbase, voff) do { _Pragma("unroll") for (int _i = 0; _i < 2; ++_i) \
;         __builtin_amdgcn_global_load_lds((const unsigned*)((const char*)(gbase) + (voff)[_i]), (PG8_LAS unsigned*)(lds + (bufoff) + ldsw + _i * 8192), 16, 0, 0); } while (0)
; #define PG8_LDA(dst, b, h) do { _Pragma("unroll") for (int m = 0; m < 4; ++m) _Pragma("unroll") for (int k = 0; k < 2; ++k) dst[m][k] = *(const PG8_LAS bf16x8*)(lds + PG8_SA(b, h) + aoff + m * 2048 + k * 1024); } while (0)
; #define PG8_LDB(dst, b, h) do { _Pragma("unroll") for (int n = 0; n < 2; ++n) _Pragma("unroll") for (int k = 0; k < 2; ++k) dst[n][k] = *(const PG8_LAS bf16x8*)(lds + PG8_SB(b, h) + boff + n * 2048 + k * 1024); } while (0)
; #define PG8_MMA(ai, bj, At, Bt) do { __builtin_amdgcn_s_setprio(1); _Pragma("unroll") for (int m = 0; m < 4; ++m) _Pragma("unroll") for (int n = 0; n < 2; ++n) _Pragma("unroll") for (int k = 0; k < 2; ++k) \
;         acc[ai][bj][m][n] = __builtin_amdgcn_mfma_f32_16x16x32_bf16(Bt[n][k], At[m][k], acc[ai][bj][m][n], 0, 0, 0); __builtin_amdgcn_s_setprio(0); } while (0)
; #define PG8_WAIT_V(n) asm volatile("s_waitcnt vmcnt(" #n ")" ::: "memory")
; #define PG8_WAIT_L(n) asm volatile("s_waitcnt lgkmcnt(" #n ")" ::: "memory")
; #define PG8_BAR __builtin_amdgcn_s_barrier()
; #define PG8_SCHED __builtin_amdgcn_sched_barrier(0)
; template <class Epi, class Sched, bool ALIGN_EPI = false, bool SP2 = false>
; __device__ __forceinline__ void gemm_phase(PG8_LAS unsigned char* lds, const Gemm g, const Sched& S, const Epi& E) {
;     ...
;             const char* a1 = cA + (size_t)(t + 1) * kstep;
;             const char* a2 = last ? nA : cA + (size_t)(t + 2) * kstep; const char* b2 = last ? nB : cB + (size_t)(t + 2) * kstep;
;             const char* a3 = a2 + kstep; const char* b3 = b2 + kstep;
;             if (last && has_next) S.a_ready(nxt);
;             if constexpr (SP2) {
;             PG8_LDB(B0, 0, 0); PG8_LDB(B1, 0, 1); PG8_SCHED; PG8_LDA(At, 0, 0); PG8_STAGE(PG8_SA(1, 1), a1 + hstepA, voffA);
;             PG8_WAIT_V(8); PG8_WAIT_L(0); PG8_BAR; PG8_MMA(0, 0, At, B0); PG8_MMA(0, 1, At, B1); PG8_BAR; PG8_SCHED;
;             PG8_LDA(At, 0, 1); PG8_STAGE(PG8_SB(0, 0), b2, voffB); PG8_STAGE(PG8_SB(0, 1), b2 + hstepB, voffB); PG8_STAGE(PG8_SA(0, 0), a2, voffA);
.LBB0_1383:
	s_add_u32 s6, s26, 0x100
	s_addc_u32 s7, s27, 0
	s_add_i32 s2, s17, 0x100
	s_cmp_eq_u32 s65, 4
	s_cselect_b32 s41, s15, s7
	s_cselect_b32 s40, s14, s6
	v_add_u32_e32 v145, s2, v142
	s_cselect_b32 s39, s13, s63
	s_cselect_b32 s38, s61, s62
	s_add_i32 s33, s24, 0x100
	ds_read_b128 v[146:149], v145
	ds_read_b128 v[150:153], v145 offset:1024
	ds_read_b128 v[154:157], v145 offset:2048
	ds_read_b128 v[158:161], v145 offset:3072
	v_add_u32_e32 v145, s33, v142
	ds_read_b128 v[162:165], v145
	ds_read_b128 v[166:169], v145 offset:1024
	ds_read_b128 v[170:173], v145 offset:2048
	ds_read_b128 v[174:177], v145 offset:3072
	v_lshl_add_u64 v[194:195], s[26:27], 0, v[138:139]
	s_add_i32 m0, s47, 0xc000
	ds_read_b128 v[178:181], v144
	ds_read_b128 v[182:185], v144 offset:1024
	ds_read_b128 v[186:189], v144 offset:2048
	ds_read_b128 v[190:193], v144 offset:3072
	ds_read_b128 v[210:213], v144 offset:4096
	ds_read_b128 v[228:231], v144 offset:5120
	ds_read_b128 v[232:235], v144 offset:6144
	ds_read_b128 v[236:239], v144 offset:7168
	global_load_lds_dwordx4 v[194:195], off
	v_lshl_add_u64 v[194:195], s[26:27], 0, v[140:141]
	s_add_i32 m0, s47, 0xe000
	s_nop 0
	global_load_lds_dwordx4 v[194:195], off
	s_waitcnt vmcnt(8)
	s_waitcnt lgkmcnt(0)
	s_barrier
	s_setprio 1
	s_waitcnt lgkmcnt(0)
	v_mfma_f32_16x16x32_bf16 v[126:129], v[146:149], v[178:181], v[126:129]
	v_mfma_f32_16x16x32_bf16 v[126:129], v[150:153], v[182:185], v[126:129]
	v_mfma_f32_16x16x32_bf16 v[122:125], v[158:161], v[182:185], v[122:125]
	v_mfma_f32_16x16x32_bf16 v[122:125], v[154:157], v[178:181], v[122:125]
	v_mfma_f32_16x16x32_bf16 v[114:117], v[154:157], v[186:189], v[114:117]
	v_mfma_f32_16x16x32_bf16 v[114:117], v[158:161], v[190:193], v[114:117]
	v_mfma_f32_16x16x32_bf16 v[118:121], v[150:153], v[190:193], v[118:121]
	v_mfma_f32_16x16x32_bf16 v[118:121], v[146:149], v[186:189], v[118:121]
	v_mfma_f32_16x16x32_bf16 v[102:105], v[146:149], v[210:213], v[102:105]
	v_mfma_f32_16x16x32_bf16 v[102:105], v[150:153], v[228:231], v[102:105]
	v_mfma_f32_16x16x32_bf16 v[98:101], v[158:161], v[228:231], v[98:101]
	v_mfma_f32_16x16x32_bf16 v[98:101], v[154:157], v[210:213], v[98:101]
	v_mfma_f32_16x16x32_bf16 v[82:85], v[154:157], v[232:235], v[82:85]
	v_mfma_f32_16x16x32_bf16 v[82:85], v[158:161], v[236:239], v[82:85]
	v_mfma_f32_16x16x32_bf16 v[86:89], v[150:153], v[236:239], v[86:89]
	v_mfma_f32_16x16x32_bf16 v[86:89], v[146:149], v[232:235], v[86:89]
	s_setprio 0
	s_setprio 1
	v_mfma_f32_16x16x32_bf16 v[110:113], v[162:165], v[178:181], v[110:113]
	v_mfma_f32_16x16x32_bf16 v[110:113], v[166:169], v[182:185], v[110:113]
	v_mfma_f32_16x16x32_bf16 v[106:109], v[174:177], v[182:185], v[106:109]
	v_mfma_f32_16x16x32_bf16 v[106:109], v[170:173], v[178:181], v[106:109]
	v_mfma_f32_16x16x32_bf16 v[90:93], v[170:173], v[186:189], v[90:93]
	v_mfma_f32_16x16x32_bf16 v[90:93], v[174:177], v[190:193], v[90:93]
	v_mfma_f32_16x16x32_bf16 v[94:97], v[166:169], v[190:193], v[94:97]
	v_mfma_f32_16x16x32_bf16 v[94:97], v[162:165], v[186:189], v[94:97]
	v_mfma_f32_16x16x32_bf16 v[78:81], v[162:165], v[210:213], v[78:81]
	v_mfma_f32_16x16x32_bf16 v[78:81], v[166:169], v[228:231], v[78:81]
	v_mfma_f32_16x16x32_bf16 v[74:77], v[174:177], v[228:231], v[74:77]
	v_mfma_f32_16x16x32_bf16 v[74:77], v[170:173], v[210:213], v[74:77]
	v_mfma_f32_16x16x32_bf16 v[66:69], v[170:173], v[232:235], v[66:69]
	v_mfma_f32_16x16x32_bf16 v[66:69], v[174:177], v[236:239], v[66:69]
	v_mfma_f32_16x16x32_bf16 v[70:73], v[166:169], v[236:239], v[70:73]
	v_mfma_f32_16x16x32_bf16 v[70:73], v[162:165], v[232:235], v[70:73]
	s_setprio 0
	s_barrier
	s_add_i32 s2, s2, s46
	v_lshl_add_u64 v[194:195], s[38:39], 0, v[0:1]
	s_mov_b32 m0, s2
	ds_read_b128 v[178:181], v144 offset:16384
	ds_read_b128 v[182:185], v144 offset:17408
	ds_read_b128 v[186:189], v144 offset:18432
	ds_read_b128 v[190:193], v144 offset:19456
	ds_read_b128 v[210:213], v144 offset:20480
	ds_read_b128 v[228:231], v144 offset:21504
	ds_read_b128 v[232:235], v144 offset:22528
	ds_read_b128 v[236:239], v144 offset:23552
	global_load_lds_dwordx4 v[194:195], off
	s_add_i32 m0, s2, 0x2000
	s_add_u32 s26, s38, 0x20000
	v_lshl_add_u64 v[214:215], s[38:39], 0, v[132:133]
	s_addc_u32 s27, s39, 0
	s_add_i32 s2, s33, s46
	global_load_lds_dwordx4 v[214:215], off
	v_lshl_add_u64 v[222:223], s[26:27], 0, v[0:1]
	s_mov_b32 m0, s2
	v_lshl_add_u64 v[224:225], s[40:41], 0, v[134:135]
	global_load_lds_dwordx4 v[222:223], off
	v_lshl_add_u64 v[222:223], s[26:27], 0, v[132:133]
	s_add_i32 m0, s2, 0x2000
	s_nop 0
	global_load_lds_dwordx4 v[222:223], off
	v_lshl_add_u64 v[222:223], s[40:41], 0, v[136:137]
	s_mov_b32 m0, s47
	s_nop 0
	global_load_lds_dwordx4 v[222:223], off
	s_mov_b32 m0, s48
	s_nop 0
	global_load_lds_dwordx4 v[224:225], off
	s_waitcnt vmcnt(8)
	s_waitcnt lgkmcnt(0)
	s_barrier
; #define PG8_STAGE(bufoff, gbase, voff) do { _Pragma("unroll") for (int _i = 0; _i < 2; ++_i) \
;         __builtin_amdgcn_global_load_lds((const unsigned*)((const char*)(gbase) + (voff)[_i]), (PG8_LAS unsigned*)(lds + (bufoff) + ldsw + _i * 8192), 16, 0, 0); } while (0)
; #define PG8_LDA(dst, b, h) do { _Pragma("unroll") for (int m = 0; m < 4; ++m) _Pragma("unroll") for (int k = 0; k < 2; ++k) dst[m][k] = *(const PG8_LAS bf16x8*)(lds + PG8_SA(b, h) + aoff + m * 2048 + k * 1024); } while (0)
; #define PG8_LDB(dst, b, h) do { _Pragma("unroll") for (int n = 0; n < 2; ++n) _Pragma("unroll") for (int k = 0; k < 2; ++k) dst[n][k] = *(const PG8_LAS bf16x8*)(lds + PG8_SB(b, h) + boff + n * 2048 + k * 1024); } while (0)
; #define PG8_MMA(ai, bj, At, Bt) do { __builtin_amdgcn_s_setprio(1); _Pragma("unroll") for (int m = 0; m < 4; ++m) _Pragma("unroll") for (int n = 0; n < 2; ++n) _Pragma("unroll") for (int k = 0; k < 2; ++k) \
;         acc[ai][bj][m][n] = __builtin_amdgcn_mfma_f32_16x16x32_bf16(Bt[n][k], At[m][k], acc[ai][bj][m][n], 0, 0, 0); __builtin_amdgcn_s_setprio(0); } while (0)
; #define PG8_WAIT_V(n) asm volatile("s_waitcnt vmcnt(" #n ")" ::: "memory")
; #define PG8_WAIT_L(n) asm volatile("s_waitcnt lgkmcnt(" #n ")" ::: "memory")
; #define PG8_BAR __builtin_amdgcn_s_barrier()
; #define PG8_SCHED __builtin_amdgcn_sched_barrier(0)
; template <class Epi, class Sched, bool ALIGN_EPI = false, bool SP2 = false>
; __device__ __forceinline__ void gemm_phase(PG8_LAS unsigned char* lds, const Gemm g, const Sched& S, const Epi& E) {
;     ...
;             PG8_WAIT_V(8); PG8_WAIT_L(0); PG8_BAR; PG8_MMA(1, 0, At, B0); PG8_MMA(1, 1, At, B1); PG8_BAR; PG8_SCHED;
;             PG8_LDB(B0, 1, 0); PG8_LDB(B1, 1, 1); PG8_SCHED; PG8_LDA(At, 1, 0); PG8_STAGE(PG8_SA(0, 1), a2 + hstepA, voffA);
;             PG8_WAIT_V(8); PG8_WAIT_L(0); PG8_BAR; PG8_MMA(0, 0, At, B0); PG8_MMA(0, 1, At, B1); PG8_BAR; PG8_SCHED;
	s_setprio 1
	s_waitcnt lgkmcnt(0)
	v_mfma_f32_16x16x32_bf16 v[62:65], v[146:149], v[178:181], v[62:65]
	v_mfma_f32_16x16x32_bf16 v[62:65], v[150:153], v[182:185], v[62:65]
	v_mfma_f32_16x16x32_bf16 v[58:61], v[158:161], v[182:185], v[58:61]
	v_mfma_f32_16x16x32_bf16 v[58:61], v[154:157], v[178:181], v[58:61]
	v_mfma_f32_16x16x32_bf16 v[50:53], v[154:157], v[186:189], v[50:53]
	v_mfma_f32_16x16x32_bf16 v[50:53], v[158:161], v[190:193], v[50:53]
	v_mfma_f32_16x16x32_bf16 v[54:57], v[150:153], v[190:193], v[54:57]
	v_mfma_f32_16x16x32_bf16 v[54:57], v[146:149], v[186:189], v[54:57]
	v_mfma_f32_16x16x32_bf16 v[38:41], v[146:149], v[210:213], v[38:41]
	v_mfma_f32_16x16x32_bf16 v[38:41], v[150:153], v[228:231], v[38:41]
	v_mfma_f32_16x16x32_bf16 v[34:37], v[158:161], v[228:231], v[34:37]
	v_mfma_f32_16x16x32_bf16 v[34:37], v[154:157], v[210:213], v[34:37]
	v_mfma_f32_16x16x32_bf16 v[18:21], v[154:157], v[232:235], v[18:21]
	v_mfma_f32_16x16x32_bf16 v[18:21], v[158:161], v[236:239], v[18:21]
	v_mfma_f32_16x16x32_bf16 v[22:25], v[150:153], v[236:239], v[22:25]
	v_mfma_f32_16x16x32_bf16 v[22:25], v[146:149], v[232:235], v[22:25]
	s_setprio 0
	s_setprio 1
	v_mfma_f32_16x16x32_bf16 v[46:49], v[162:165], v[178:181], v[46:49]
	v_mfma_f32_16x16x32_bf16 v[46:49], v[166:169], v[182:185], v[46:49]
	v_mfma_f32_16x16x32_bf16 v[42:45], v[174:177], v[182:185], v[42:45]
	v_mfma_f32_16x16x32_bf16 v[42:45], v[170:173], v[178:181], v[42:45]
	v_mfma_f32_16x16x32_bf16 v[26:29], v[170:173], v[186:189], v[26:29]
	v_mfma_f32_16x16x32_bf16 v[26:29], v[174:177], v[190:193], v[26:29]
	v_mfma_f32_16x16x32_bf16 v[30:33], v[166:169], v[190:193], v[30:33]
	v_mfma_f32_16x16x32_bf16 v[30:33], v[162:165], v[186:189], v[30:33]
	v_mfma_f32_16x16x32_bf16 v[14:17], v[162:165], v[210:213], v[14:17]
	v_mfma_f32_16x16x32_bf16 v[14:17], v[166:169], v[228:231], v[14:17]
	v_mfma_f32_16x16x32_bf16 v[10:13], v[174:177], v[228:231], v[10:13]
	v_mfma_f32_16x16x32_bf16 v[10:13], v[170:173], v[210:213], v[10:13]
	v_mfma_f32_16x16x32_bf16 v[2:5], v[170:173], v[232:235], v[2:5]
	v_mfma_f32_16x16x32_bf16 v[2:5], v[174:177], v[236:239], v[2:5]
	v_mfma_f32_16x16x32_bf16 v[6:9], v[166:169], v[236:239], v[6:9]
	v_mfma_f32_16x16x32_bf16 v[6:9], v[162:165], v[232:235], v[6:9]
	s_setprio 0
	s_barrier
	s_add_i32 s2, s87, 0x100
	v_add_u32_e32 v145, s2, v142
	s_add_i32 s33, s69, 0x100
	ds_read_b128 v[146:149], v145
	ds_read_b128 v[150:153], v145 offset:1024
	ds_read_b128 v[154:157], v145 offset:2048
	ds_read_b128 v[158:161], v145 offset:3072
	v_add_u32_e32 v145, s33, v142
	ds_read_b128 v[162:165], v145
	ds_read_b128 v[166:169], v145 offset:1024
	ds_read_b128 v[170:173], v145 offset:2048
	ds_read_b128 v[174:177], v145 offset:3072
	s_add_u32 s26, s40, 0x130000
	s_addc_u32 s27, s41, 0
	s_mov_b32 m0, s49
	v_lshl_add_u64 v[240:241], s[26:27], 0, v[136:137]
	ds_read_b128 v[178:181], v144 offset:32768
	ds_read_b128 v[182:185], v144 offset:33792
	ds_read_b128 v[186:189], v144 offset:34816
	ds_read_b128 v[190:193], v144 offset:35840
	ds_read_b128 v[210:213], v144 offset:36864
	ds_read_b128 v[228:231], v144 offset:37888
	ds_read_b128 v[232:235], v144 offset:38912
	ds_read_b128 v[236:239], v144 offset:39936
	global_load_lds_dwordx4 v[240:241], off
	v_lshl_add_u64 v[240:241], s[26:27], 0, v[134:135]
	s_mov_b32 m0, s50
	s_nop 0
	global_load_lds_dwordx4 v[240:241], off
	s_waitcnt vmcnt(8)
	s_waitcnt lgkmcnt(0)
	s_barrier
	s_setprio 1
	s_waitcnt lgkmcnt(0)
	v_mfma_f32_16x16x32_bf16 v[126:129], v[146:149], v[178:181], v[126:129]
	v_mfma_f32_16x16x32_bf16 v[126:129], v[150:153], v[182:185], v[126:129]
	v_mfma_f32_16x16x32_bf16 v[122:125], v[158:161], v[182:185], v[122:125]
	v_mfma_f32_16x16x32_bf16 v[122:125], v[154:157], v[178:181], v[122:125]
	v_mfma_f32_16x16x32_bf16 v[114:117], v[154:157], v[186:189], v[114:117]
	v_mfma_f32_16x16x32_bf16 v[114:117], v[158:161], v[190:193], v[114:117]
	v_mfma_f32_16x16x32_bf16 v[118:121], v[150:153], v[190:193], v[118:121]
	v_mfma_f32_16x16x32_bf16 v[118:121], v[146:149], v[186:189], v[118:121]
	v_mfma_f32_16x16x32_bf16 v[102:105], v[146:149], v[210:213], v[102:105]
	v_mfma_f32_16x16x32_bf16 v[102:105], v[150:153], v[228:231], v[102:105]
	v_mfma_f32_16x16x32_bf16 v[98:101], v[158:161], v[228:231], v[98:101]
	v_mfma_f32_16x16x32_bf16 v[98:101], v[154:157], v[210:213], v[98:101]
	v_mfma_f32_16x16x32_bf16 v[82:85], v[154:157], v[232:235], v[82:85]
	v_mfma_f32_16x16x32_bf16 v[82:85], v[158:161], v[236:239], v[82:85]
	v_mfma_f32_16x16x32_bf16 v[86:89], v[150:153], v[236:239], v[86:89]
	v_mfma_f32_16x16x32_bf16 v[86:89], v[146:149], v[232:235], v[86:89]
	s_setprio 0
	s_setprio 1
	v_mfma_f32_16x16x32_bf16 v[110:113], v[162:165], v[178:181], v[110:113]
	v_mfma_f32_16x16x32_bf16 v[110:113], v[166:169], v[182:185], v[110:113]
	v_mfma_f32_16x16x32_bf16 v[106:109], v[174:177], v[182:185], v[106:109]
	v_mfma_f32_16x16x32_bf16 v[106:109], v[170:173], v[178:181], v[106:109]
	v_mfma_f32_16x16x32_bf16 v[90:93], v[170:173], v[186:189], v[90:93]
	v_mfma_f32_16x16x32_bf16 v[90:93], v[174:177], v[190:193], v[90:93]
	v_mfma_f32_16x16x32_bf16 v[94:97], v[166:169], v[190:193], v[94:97]
	v_mfma_f32_16x16x32_bf16 v[94:97], v[162:165], v[186:189], v[94:97]
	v_mfma_f32_16x16x32_bf16 v[78:81], v[162:165], v[210:213], v[78:81]
	v_mfma_f32_16x16x32_bf16 v[78:81], v[166:169], v[228:231], v[78:81]
	v_mfma_f32_16x16x32_bf16 v[74:77], v[174:177], v[228:231], v[74:77]
	v_mfma_f32_16x16x32_bf16 v[74:77], v[170:173], v[210:213], v[74:77]
	v_mfma_f32_16x16x32_bf16 v[66:69], v[170:173], v[232:235], v[66:69]
	v_mfma_f32_16x16x32_bf16 v[66:69], v[174:177], v[236:239], v[66:69]
	v_mfma_f32_16x16x32_bf16 v[70:73], v[166:169], v[236:239], v[70:73]
	v_mfma_f32_16x16x32_bf16 v[70:73], v[162:165], v[232:235], v[70:73]
	s_setprio 0
	s_barrier
; #define PG8_STAGE(bufoff, gbase, voff) do { _Pragma("unroll") for (int _i = 0; _i < 2; ++_i) \
;         __builtin_amdgcn_global_load_lds((const unsigned*)((const char*)(gbase) + (voff)[_i]), (PG8_LAS unsigned*)(lds + (bufoff) + ldsw + _i * 8192), 16, 0, 0); } while (0)
; #define PG8_LDA(dst, b, h) do { _Pragma("unroll") for (int m = 0; m < 4; ++m) _Pragma("unroll") for (int k = 0; k < 2; ++k) dst[m][k] = *(const PG8_LAS bf16x8*)(lds + PG8_SA(b, h) + aoff + m * 2048 + k * 1024); } while (0)
; #define PG8_MMA(ai, bj, At, Bt) do { __builtin_amdgcn_s_setprio(1); _Pragma("unroll") for (int m = 0; m < 4; ++m) _Pragma("unroll") for (int n = 0; n < 2; ++n) _Pragma("unroll") for (int k = 0; k < 2; ++k) \
;         acc[ai][bj][m][n] = __builtin_amdgcn_mfma_f32_16x16x32_bf16(Bt[n][k], At[m][k], acc[ai][bj][m][n], 0, 0, 0); __builtin_amdgcn_s_setprio(0); } while (0)
; #define PG8_WAIT_V(n) asm volatile("s_waitcnt vmcnt(" #n ")" ::: "memory")
; #define PG8_WAIT_L(n) asm volatile("s_waitcnt lgkmcnt(" #n ")" ::: "memory")
; #define PG8_BAR __builtin_amdgcn_s_barrier()
; #define PG8_SCHED __builtin_amdgcn_sched_barrier(0)
; template <class Epi, class Sched, bool ALIGN_EPI = false, bool SP2 = false>
; __device__ __forceinline__ void gemm_phase(PG8_LAS unsigned char* lds, const Gemm g, const Sched& S, const Epi& E) {
;     ...
;             PG8_LDA(At, 1, 1); PG8_STAGE(PG8_SB(1, 0), b3, voffB); PG8_STAGE(PG8_SB(1, 1), b3 + hstepB, voffB); PG8_STAGE(PG8_SA(1, 0), a3, voffA);
;             PG8_WAIT_V(8); PG8_WAIT_L(0); PG8_BAR; PG8_MMA(1, 0, At, B0); PG8_MMA(1, 1, At, B1); PG8_BAR; PG8_SCHED;
;     ...
;         if constexpr (ALIGN_EPI) { if (wr == 0) PG8_BAR; }
	s_add_i32 s2, s2, s46
	v_lshl_add_u64 v[194:195], v[194:195], 0, s[94:95]
	s_mov_b32 m0, s2
	ds_read_b128 v[178:181], v144 offset:49152
	ds_read_b128 v[182:185], v144 offset:50176
	ds_read_b128 v[186:189], v144 offset:51200
	ds_read_b128 v[190:193], v144 offset:52224
	ds_read_b128 v[210:213], v144 offset:53248
	ds_read_b128 v[228:231], v144 offset:54272
	ds_read_b128 v[232:235], v144 offset:55296
	ds_read_b128 v[236:239], v144 offset:56320
	global_load_lds_dwordx4 v[194:195], off
	s_add_i32 m0, s2, 0x2000
	s_add_u32 s26, s38, 0x20080
	v_lshl_add_u64 v[194:195], v[214:215], 0, s[94:95]
	s_addc_u32 s27, s39, 0
	s_add_i32 s2, s33, s46
	global_load_lds_dwordx4 v[194:195], off
	v_lshl_add_u64 v[194:195], s[26:27], 0, v[0:1]
	s_mov_b32 m0, s2
	s_nop 0
	global_load_lds_dwordx4 v[194:195], off
	v_lshl_add_u64 v[194:195], s[26:27], 0, v[132:133]
	s_add_i32 m0, s2, 0x2000
	s_nop 0
	global_load_lds_dwordx4 v[194:195], off
	v_lshl_add_u64 v[194:195], v[222:223], 0, s[94:95]
	s_mov_b32 m0, s51
	s_nop 0
	global_load_lds_dwordx4 v[194:195], off
	v_lshl_add_u64 v[194:195], v[224:225], 0, s[94:95]
	s_mov_b32 m0, s58
	s_nop 0
	global_load_lds_dwordx4 v[194:195], off
	s_waitcnt vmcnt(8)
	s_waitcnt lgkmcnt(0)
	s_barrier
	s_setprio 1
	s_waitcnt lgkmcnt(0)
	v_mfma_f32_16x16x32_bf16 v[62:65], v[146:149], v[178:181], v[62:65]
	v_mfma_f32_16x16x32_bf16 v[62:65], v[150:153], v[182:185], v[62:65]
	v_mfma_f32_16x16x32_bf16 v[58:61], v[158:161], v[182:185], v[58:61]
	v_mfma_f32_16x16x32_bf16 v[58:61], v[154:157], v[178:181], v[58:61]
	v_mfma_f32_16x16x32_bf16 v[50:53], v[154:157], v[186:189], v[50:53]
	v_mfma_f32_16x16x32_bf16 v[50:53], v[158:161], v[190:193], v[50:53]
	v_mfma_f32_16x16x32_bf16 v[54:57], v[150:153], v[190:193], v[54:57]
	v_mfma_f32_16x16x32_bf16 v[54:57], v[146:149], v[186:189], v[54:57]
	v_mfma_f32_16x16x32_bf16 v[38:41], v[146:149], v[210:213], v[38:41]
	v_mfma_f32_16x16x32_bf16 v[38:41], v[150:153], v[228:231], v[38:41]
	v_mfma_f32_16x16x32_bf16 v[34:37], v[158:161], v[228:231], v[34:37]
	v_mfma_f32_16x16x32_bf16 v[34:37], v[154:157], v[210:213], v[34:37]
	v_mfma_f32_16x16x32_bf16 v[18:21], v[154:157], v[232:235], v[18:21]
	v_mfma_f32_16x16x32_bf16 v[18:21], v[158:161], v[236:239], v[18:21]
	v_mfma_f32_16x16x32_bf16 v[22:25], v[150:153], v[236:239], v[22:25]
	v_mfma_f32_16x16x32_bf16 v[22:25], v[146:149], v[232:235], v[22:25]
	s_setprio 0
	s_setprio 1
	v_mfma_f32_16x16x32_bf16 v[46:49], v[162:165], v[178:181], v[46:49]
	v_mfma_f32_16x16x32_bf16 v[46:49], v[166:169], v[182:185], v[46:49]
	v_mfma_f32_16x16x32_bf16 v[42:45], v[174:177], v[182:185], v[42:45]
	v_mfma_f32_16x16x32_bf16 v[42:45], v[170:173], v[178:181], v[42:45]
	v_mfma_f32_16x16x32_bf16 v[26:29], v[170:173], v[186:189], v[26:29]
	v_mfma_f32_16x16x32_bf16 v[26:29], v[174:177], v[190:193], v[26:29]
	v_mfma_f32_16x16x32_bf16 v[30:33], v[166:169], v[190:193], v[30:33]
	v_mfma_f32_16x16x32_bf16 v[30:33], v[162:165], v[186:189], v[30:33]
	v_mfma_f32_16x16x32_bf16 v[14:17], v[162:165], v[210:213], v[14:17]
	v_mfma_f32_16x16x32_bf16 v[14:17], v[166:169], v[228:231], v[14:17]
	v_mfma_f32_16x16x32_bf16 v[10:13], v[174:177], v[228:231], v[10:13]
	v_mfma_f32_16x16x32_bf16 v[10:13], v[170:173], v[210:213], v[10:13]
	v_mfma_f32_16x16x32_bf16 v[2:5], v[170:173], v[232:235], v[2:5]
	v_mfma_f32_16x16x32_bf16 v[2:5], v[174:177], v[236:239], v[2:5]
	v_mfma_f32_16x16x32_bf16 v[6:9], v[166:169], v[236:239], v[6:9]
	v_mfma_f32_16x16x32_bf16 v[6:9], v[162:165], v[232:235], v[6:9]
	s_setprio 0
	s_barrier
	s_add_i32 s65, s65, 2
	s_add_u32 s62, s62, 0x100
	s_addc_u32 s63, s63, 0
	s_cmp_gt_u32 s65, 5
	s_mov_b64 s[26:27], s[6:7]
	s_cbranch_scc0 .LBB0_1383
	s_and_b64 vcc, exec, s[10:11]
	s_cbranch_vccz .LBB0_1386
	s_barrier

; #define PG8_STAGE(bufoff, gbase, voff) do { _Pragma("unroll") for (int _i = 0; _i < 2; ++_i) \
;         __builtin_amdgcn_global_load_lds((const unsigned*)((const char*)(gbase) + (voff)[_i]), (PG8_LAS unsigned*)(lds + (bufoff) + ldsw + _i * 8192), 16, 0, 0); } while (0)
; #define PG8_LDA(dst, b, h) do { _Pragma("unroll") for (int m = 0; m < 4; ++m) _Pragma("unroll") for (int k = 0; k < 2; ++k) dst[m][k] = *(const PG8_LAS bf16x8*)(lds + PG8_SA(b, h) + aoff + m * 2048 + k * 1024); } while (0)
; #define PG8_LDB(dst, b, h) do { _Pragma("unroll") for (int n = 0; n < 2; ++n) _Pragma("unroll") for (int k = 0; k < 2; ++k) dst[n][k] = *(const PG8_LAS bf16x8*)(lds + PG8_SB(b, h) + boff + n * 2048 + k * 1024); } while (0)
; #define PG8_MMA(ai, bj, At, Bt) do { __builtin_amdgcn_s_setprio(1); _Pragma("unroll") for (int m = 0; m < 4; ++m) _Pragma("unroll") for (int n = 0; n < 2; ++n) _Pragma("unroll") for (int k = 0; k < 2; ++k) \
;         acc[ai][bj][m][n] = __builtin_amdgcn_mfma_f32_16x16x32_bf16(Bt[n][k], At[m][k], acc[ai][bj][m][n], 0, 0, 0); __builtin_amdgcn_s_setprio(0); } while (0)
; #define PG8_WAIT_V(n) asm volatile("s_waitcnt vmcnt(" #n ")" ::: "memory")
; #define PG8_WAIT_L(n) asm volatile("s_waitcnt lgkmcnt(" #n ")" ::: "memory")
; #define PG8_BAR __builtin_amdgcn_s_barrier()
; #define PG8_SCHED __builtin_amdgcn_sched_barrier(0)
; template <class Epi, class Sched, bool ALIGN_EPI = false, bool SP2 = false>
; __device__ __forceinline__ void gemm_phase(PG8_LAS unsigned char* lds, const Gemm g, const Sched& S, const Epi& E) {
;     ...
;             const char* a1 = cA + (size_t)(t + 1) * kstep;
;             const char* a2 = last ? nA : cA + (size_t)(t + 2) * kstep; const char* b2 = last ? nB : cB + (size_t)(t + 2) * kstep;
;             const char* a3 = a2 + kstep; const char* b3 = b2 + kstep;
;             if (last && has_next) S.a_ready(nxt);
;             if constexpr (SP2) {
;             PG8_LDB(B0, 0, 0); PG8_LDB(B1, 0, 1); PG8_SCHED; PG8_LDA(At, 0, 0); PG8_STAGE(PG8_SA(1, 1), a1 + hstepA, voffA);
;             PG8_WAIT_V(8); PG8_WAIT_L(0); PG8_BAR; PG8_MMA(0, 0, At, B0); PG8_MMA(0, 1, At, B1); PG8_BAR; PG8_SCHED;
;             PG8_LDA(At, 0, 1); PG8_STAGE(PG8_SB(0, 0), b2, voffB); PG8_STAGE(PG8_SB(0, 1), b2 + hstepB, voffB); PG8_STAGE(PG8_SA(0, 0), a2, voffA);
.LBB0_1403:
	s_add_u32 s2, s38, s44
	s_addc_u32 s33, s39, 0
	s_add_u32 s45, s2, 0x100
	s_addc_u32 s48, s33, 0
	s_and_b64 s[46:47], s[42:43], exec
	s_cselect_b32 s47, s27, s48
	s_cselect_b32 s46, s26, s45
	s_add_u32 s44, s18, s44
	s_addc_u32 s45, s19, 0
	s_add_u32 s44, s44, 0x100
	s_addc_u32 s45, s45, 0
	s_add_i32 s68, s17, 0x100
	s_and_b64 s[42:43], s[42:43], exec
	s_cselect_b32 s49, s15, s45
	s_cselect_b32 s48, s91, s44
	s_add_i32 s43, s24, 0x100
	s_add_u32 s52, s2, 0x130080
	s_addc_u32 s53, s33, 0
	s_add_i32 s84, s68, s59
	s_add_i32 m0, s82, 0xc000
	s_add_i32 s70, s82, 0xe000
	s_add_i32 s79, s84, 0x2000
	v_add_u32_e32 v141, s68, v138
	s_add_u32 s50, s48, 0x10000
	ds_read_b128 v[142:145], v141
	ds_read_b128 v[146:149], v141 offset:1024
	ds_read_b128 v[150:153], v141 offset:2048
	ds_read_b128 v[154:157], v141 offset:3072
	v_add_u32_e32 v141, s43, v138
	s_addc_u32 s51, s49, 0
	s_add_i32 s85, s43, s59
	ds_read_b128 v[158:161], v141
	ds_read_b128 v[162:165], v141 offset:1024
	ds_read_b128 v[166:169], v141 offset:2048
	ds_read_b128 v[170:173], v141 offset:3072
	s_add_i32 s78, s85, 0x2000
	s_add_i32 vcc_hi, s87, 0x100
	s_add_i32 s2, s69, 0x100
	s_add_u32 s44, s46, 0x130000
	s_addc_u32 s45, s47, 0
	s_add_i32 vcc_lo, vcc_hi, s59
	s_add_i32 s86, vcc_lo, 0x2000
	s_add_u32 s42, s48, 0x10080
	s_addc_u32 s43, s49, 0
	s_add_i32 s33, s2, s59
	s_add_i32 s68, s33, 0x2000
	v_lshl_add_u64 v[194:195], s[52:53], 0, v[136:137]
	ds_read_b128 v[174:177], v140
	ds_read_b128 v[178:181], v140 offset:1024
	ds_read_b128 v[182:185], v140 offset:2048
	ds_read_b128 v[186:189], v140 offset:3072
	ds_read_b128 v[190:193], v140 offset:4096
	ds_read_b128 v[210:213], v140 offset:5120
	ds_read_b128 v[228:231], v140 offset:6144
	ds_read_b128 v[232:235], v140 offset:7168
	global_load_lds_dwordx4 v[194:195], off
	v_lshl_add_u64 v[194:195], s[52:53], 0, v[134:135]
	s_mov_b32 m0, s70
	s_nop 0
	global_load_lds_dwordx4 v[194:195], off
	s_waitcnt vmcnt(8)
	s_waitcnt lgkmcnt(0)
	s_barrier
	s_setprio 1
	s_waitcnt lgkmcnt(0)
	v_mfma_f32_16x16x32_bf16 v[126:129], v[142:145], v[174:177], v[126:129]
	v_mfma_f32_16x16x32_bf16 v[126:129], v[146:149], v[178:181], v[126:129]
	v_mfma_f32_16x16x32_bf16 v[122:125], v[154:157], v[178:181], v[122:125]
	v_mfma_f32_16x16x32_bf16 v[122:125], v[150:153], v[174:177], v[122:125]
	v_mfma_f32_16x16x32_bf16 v[114:117], v[150:153], v[182:185], v[114:117]
	v_mfma_f32_16x16x32_bf16 v[114:117], v[154:157], v[186:189], v[114:117]
	v_mfma_f32_16x16x32_bf16 v[118:121], v[146:149], v[186:189], v[118:121]
	v_mfma_f32_16x16x32_bf16 v[118:121], v[142:145], v[182:185], v[118:121]
	v_mfma_f32_16x16x32_bf16 v[102:105], v[142:145], v[190:193], v[102:105]
	v_mfma_f32_16x16x32_bf16 v[102:105], v[146:149], v[210:213], v[102:105]
	v_mfma_f32_16x16x32_bf16 v[98:101], v[154:157], v[210:213], v[98:101]
	v_mfma_f32_16x16x32_bf16 v[98:101], v[150:153], v[190:193], v[98:101]
	v_mfma_f32_16x16x32_bf16 v[82:85], v[150:153], v[228:231], v[82:85]
	v_mfma_f32_16x16x32_bf16 v[82:85], v[154:157], v[232:235], v[82:85]
	v_mfma_f32_16x16x32_bf16 v[86:89], v[146:149], v[232:235], v[86:89]
	v_mfma_f32_16x16x32_bf16 v[86:89], v[142:145], v[228:231], v[86:89]
	s_setprio 0
	s_setprio 1
	v_mfma_f32_16x16x32_bf16 v[110:113], v[158:161], v[174:177], v[110:113]
	v_mfma_f32_16x16x32_bf16 v[110:113], v[162:165], v[178:181], v[110:113]
	v_mfma_f32_16x16x32_bf16 v[106:109], v[170:173], v[178:181], v[106:109]
	v_mfma_f32_16x16x32_bf16 v[106:109], v[166:169], v[174:177], v[106:109]
	v_mfma_f32_16x16x32_bf16 v[90:93], v[166:169], v[182:185], v[90:93]
	v_mfma_f32_16x16x32_bf16 v[90:93], v[170:173], v[186:189], v[90:93]
	v_mfma_f32_16x16x32_bf16 v[94:97], v[162:165], v[186:189], v[94:97]
	v_mfma_f32_16x16x32_bf16 v[94:97], v[158:161], v[182:185], v[94:97]
	v_mfma_f32_16x16x32_bf16 v[78:81], v[158:161], v[190:193], v[78:81]
	v_mfma_f32_16x16x32_bf16 v[78:81], v[162:165], v[210:213], v[78:81]
	v_mfma_f32_16x16x32_bf16 v[74:77], v[170:173], v[210:213], v[74:77]
	v_mfma_f32_16x16x32_bf16 v[74:77], v[166:169], v[190:193], v[74:77]
	v_mfma_f32_16x16x32_bf16 v[66:69], v[166:169], v[228:231], v[66:69]
	v_mfma_f32_16x16x32_bf16 v[66:69], v[170:173], v[232:235], v[66:69]
	v_mfma_f32_16x16x32_bf16 v[70:73], v[162:165], v[232:235], v[70:73]
	v_mfma_f32_16x16x32_bf16 v[70:73], v[158:161], v[228:231], v[70:73]
	s_setprio 0
	s_barrier
	s_mov_b32 m0, s84
	v_lshl_add_u64 v[194:195], s[48:49], 0, v[0:1]
	ds_read_b128 v[174:177], v140 offset:16384
	ds_read_b128 v[178:181], v140 offset:17408
	ds_read_b128 v[182:185], v140 offset:18432
	ds_read_b128 v[186:189], v140 offset:19456
	ds_read_b128 v[190:193], v140 offset:20480
	ds_read_b128 v[210:213], v140 offset:21504
	ds_read_b128 v[228:231], v140 offset:22528
	ds_read_b128 v[232:235], v140 offset:23552
	global_load_lds_dwordx4 v[194:195], off
	v_lshl_add_u64 v[214:215], s[48:49], 0, v[132:133]
	s_mov_b32 m0, s79
	v_lshl_add_u64 v[222:223], s[50:51], 0, v[0:1]
	global_load_lds_dwordx4 v[214:215], off
	s_mov_b32 m0, s85
	v_lshl_add_u64 v[224:225], s[46:47], 0, v[134:135]
	global_load_lds_dwordx4 v[222:223], off
	v_lshl_add_u64 v[222:223], s[50:51], 0, v[132:133]
	s_mov_b32 m0, s78
	s_nop 0
	global_load_lds_dwordx4 v[222:223], off
	v_lshl_add_u64 v[222:223], s[46:47], 0, v[136:137]
	s_mov_b32 m0, s82
	s_nop 0
	global_load_lds_dwordx4 v[222:223], off
	s_mov_b32 m0, s72
	s_nop 0
	global_load_lds_dwordx4 v[224:225], off
	s_waitcnt vmcnt(8)
	s_waitcnt lgkmcnt(0)
	s_barrier
; #define PG8_STAGE(bufoff, gbase, voff) do { _Pragma("unroll") for (int _i = 0; _i < 2; ++_i) \
;         __builtin_amdgcn_global_load_lds((const unsigned*)((const char*)(gbase) + (voff)[_i]), (PG8_LAS unsigned*)(lds + (bufoff) + ldsw + _i * 8192), 16, 0, 0); } while (0)
; #define PG8_LDA(dst, b, h) do { _Pragma("unroll") for (int m = 0; m < 4; ++m) _Pragma("unroll") for (int k = 0; k < 2; ++k) dst[m][k] = *(const PG8_LAS bf16x8*)(lds + PG8_SA(b, h) + aoff + m * 2048 + k * 1024); } while (0)
; #define PG8_LDB(dst, b, h) do { _Pragma("unroll") for (int n = 0; n < 2; ++n) _Pragma("unroll") for (int k = 0; k < 2; ++k) dst[n][k] = *(const PG8_LAS bf16x8*)(lds + PG8_SB(b, h) + boff + n * 2048 + k * 1024); } while (0)
; #define PG8_MMA(ai, bj, At, Bt) do { __builtin_amdgcn_s_setprio(1); _Pragma("unroll") for (int m = 0; m < 4; ++m) _Pragma("unroll") for (int n = 0; n < 2; ++n) _Pragma("unroll") for (int k = 0; k < 2; ++k) \
;         acc[ai][bj][m][n] = __builtin_amdgcn_mfma_f32_16x16x32_bf16(Bt[n][k], At[m][k], acc[ai][bj][m][n], 0, 0, 0); __builtin_amdgcn_s_setprio(0); } while (0)
; #define PG8_WAIT_V(n) asm volatile("s_waitcnt vmcnt(" #n ")" ::: "memory")
; #define PG8_WAIT_L(n) asm volatile("s_waitcnt lgkmcnt(" #n ")" ::: "memory")
; #define PG8_BAR __builtin_amdgcn_s_barrier()
; #define PG8_SCHED __builtin_amdgcn_sched_barrier(0)
; template <class Epi, class Sched, bool ALIGN_EPI = false, bool SP2 = false>
; __device__ __forceinline__ void gemm_phase(PG8_LAS unsigned char* lds, const Gemm g, const Sched& S, const Epi& E) {
;     ...
;             PG8_WAIT_V(8); PG8_WAIT_L(0); PG8_BAR; PG8_MMA(1, 0, At, B0); PG8_MMA(1, 1, At, B1); PG8_BAR; PG8_SCHED;
;             PG8_LDB(B0, 1, 0); PG8_LDB(B1, 1, 1); PG8_SCHED; PG8_LDA(At, 1, 0); PG8_STAGE(PG8_SA(0, 1), a2 + hstepA, voffA);
;             PG8_WAIT_V(8); PG8_WAIT_L(0); PG8_BAR; PG8_MMA(0, 0, At, B0); PG8_MMA(0, 1, At, B1); PG8_BAR; PG8_SCHED;
	s_setprio 1
	s_waitcnt lgkmcnt(0)
	v_mfma_f32_16x16x32_bf16 v[62:65], v[142:145], v[174:177], v[62:65]
	v_mfma_f32_16x16x32_bf16 v[62:65], v[146:149], v[178:181], v[62:65]
	v_mfma_f32_16x16x32_bf16 v[58:61], v[154:157], v[178:181], v[58:61]
	v_mfma_f32_16x16x32_bf16 v[58:61], v[150:153], v[174:177], v[58:61]
	v_mfma_f32_16x16x32_bf16 v[50:53], v[150:153], v[182:185], v[50:53]
	v_mfma_f32_16x16x32_bf16 v[50:53], v[154:157], v[186:189], v[50:53]
	v_mfma_f32_16x16x32_bf16 v[54:57], v[146:149], v[186:189], v[54:57]
	v_mfma_f32_16x16x32_bf16 v[54:57], v[142:145], v[182:185], v[54:57]
	v_mfma_f32_16x16x32_bf16 v[38:41], v[142:145], v[190:193], v[38:41]
	v_mfma_f32_16x16x32_bf16 v[38:41], v[146:149], v[210:213], v[38:41]
	v_mfma_f32_16x16x32_bf16 v[34:37], v[154:157], v[210:213], v[34:37]
	v_mfma_f32_16x16x32_bf16 v[34:37], v[150:153], v[190:193], v[34:37]
	v_mfma_f32_16x16x32_bf16 v[18:21], v[150:153], v[228:231], v[18:21]
	v_mfma_f32_16x16x32_bf16 v[18:21], v[154:157], v[232:235], v[18:21]
	v_mfma_f32_16x16x32_bf16 v[22:25], v[146:149], v[232:235], v[22:25]
	v_mfma_f32_16x16x32_bf16 v[22:25], v[142:145], v[228:231], v[22:25]
	s_setprio 0
	s_setprio 1
	v_mfma_f32_16x16x32_bf16 v[46:49], v[158:161], v[174:177], v[46:49]
	v_mfma_f32_16x16x32_bf16 v[46:49], v[162:165], v[178:181], v[46:49]
	v_mfma_f32_16x16x32_bf16 v[42:45], v[170:173], v[178:181], v[42:45]
	v_mfma_f32_16x16x32_bf16 v[42:45], v[166:169], v[174:177], v[42:45]
	v_mfma_f32_16x16x32_bf16 v[26:29], v[166:169], v[182:185], v[26:29]
	v_mfma_f32_16x16x32_bf16 v[26:29], v[170:173], v[186:189], v[26:29]
	v_mfma_f32_16x16x32_bf16 v[30:33], v[162:165], v[186:189], v[30:33]
	v_mfma_f32_16x16x32_bf16 v[30:33], v[158:161], v[182:185], v[30:33]
	v_mfma_f32_16x16x32_bf16 v[14:17], v[158:161], v[190:193], v[14:17]
	v_mfma_f32_16x16x32_bf16 v[14:17], v[162:165], v[210:213], v[14:17]
	v_mfma_f32_16x16x32_bf16 v[10:13], v[170:173], v[210:213], v[10:13]
	v_mfma_f32_16x16x32_bf16 v[10:13], v[166:169], v[190:193], v[10:13]
	v_mfma_f32_16x16x32_bf16 v[2:5], v[166:169], v[228:231], v[2:5]
	v_mfma_f32_16x16x32_bf16 v[2:5], v[170:173], v[232:235], v[2:5]
	v_mfma_f32_16x16x32_bf16 v[6:9], v[162:165], v[232:235], v[6:9]
	v_mfma_f32_16x16x32_bf16 v[6:9], v[158:161], v[228:231], v[6:9]
	s_setprio 0
	s_barrier
	v_add_u32_e32 v141, vcc_hi, v138
	ds_read_b128 v[142:145], v141
	ds_read_b128 v[146:149], v141 offset:1024
	ds_read_b128 v[150:153], v141 offset:2048
	ds_read_b128 v[154:157], v141 offset:3072
	v_add_u32_e32 v141, s2, v138
	ds_read_b128 v[158:161], v141
	ds_read_b128 v[162:165], v141 offset:1024
	ds_read_b128 v[166:169], v141 offset:2048
	ds_read_b128 v[170:173], v141 offset:3072
	s_mov_b32 m0, s73
	v_lshl_add_u64 v[236:237], s[44:45], 0, v[136:137]
	ds_read_b128 v[174:177], v140 offset:32768
	ds_read_b128 v[178:181], v140 offset:33792
	ds_read_b128 v[182:185], v140 offset:34816
	ds_read_b128 v[186:189], v140 offset:35840
	ds_read_b128 v[190:193], v140 offset:36864
	ds_read_b128 v[210:213], v140 offset:37888
	ds_read_b128 v[228:231], v140 offset:38912
	ds_read_b128 v[232:235], v140 offset:39936
	global_load_lds_dwordx4 v[236:237], off
	v_lshl_add_u64 v[236:237], s[44:45], 0, v[134:135]
	s_mov_b32 m0, s76
	s_nop 0
	global_load_lds_dwordx4 v[236:237], off
	s_waitcnt vmcnt(8)
	s_waitcnt lgkmcnt(0)
	s_barrier
	s_setprio 1
	s_waitcnt lgkmcnt(0)
	v_mfma_f32_16x16x32_bf16 v[126:129], v[142:145], v[174:177], v[126:129]
	v_mfma_f32_16x16x32_bf16 v[126:129], v[146:149], v[178:181], v[126:129]
	v_mfma_f32_16x16x32_bf16 v[122:125], v[154:157], v[178:181], v[122:125]
	v_mfma_f32_16x16x32_bf16 v[122:125], v[150:153], v[174:177], v[122:125]
	v_mfma_f32_16x16x32_bf16 v[114:117], v[150:153], v[182:185], v[114:117]
	v_mfma_f32_16x16x32_bf16 v[114:117], v[154:157], v[186:189], v[114:117]
	v_mfma_f32_16x16x32_bf16 v[118:121], v[146:149], v[186:189], v[118:121]
	v_mfma_f32_16x16x32_bf16 v[118:121], v[142:145], v[182:185], v[118:121]
	v_mfma_f32_16x16x32_bf16 v[102:105], v[142:145], v[190:193], v[102:105]
	v_mfma_f32_16x16x32_bf16 v[102:105], v[146:149], v[210:213], v[102:105]
	v_mfma_f32_16x16x32_bf16 v[98:101], v[154:157], v[210:213], v[98:101]
	v_mfma_f32_16x16x32_bf16 v[98:101], v[150:153], v[190:193], v[98:101]
	v_mfma_f32_16x16x32_bf16 v[82:85], v[150:153], v[228:231], v[82:85]
	v_mfma_f32_16x16x32_bf16 v[82:85], v[154:157], v[232:235], v[82:85]
	v_mfma_f32_16x16x32_bf16 v[86:89], v[146:149], v[232:235], v[86:89]
	v_mfma_f32_16x16x32_bf16 v[86:89], v[142:145], v[228:231], v[86:89]
	s_setprio 0
	s_setprio 1
	v_mfma_f32_16x16x32_bf16 v[110:113], v[158:161], v[174:177], v[110:113]
	v_mfma_f32_16x16x32_bf16 v[110:113], v[162:165], v[178:181], v[110:113]
	v_mfma_f32_16x16x32_bf16 v[106:109], v[170:173], v[178:181], v[106:109]
	v_mfma_f32_16x16x32_bf16 v[106:109], v[166:169], v[174:177], v[106:109]
	v_mfma_f32_16x16x32_bf16 v[90:93], v[166:169], v[182:185], v[90:93]
	v_mfma_f32_16x16x32_bf16 v[90:93], v[170:173], v[186:189], v[90:93]
	v_mfma_f32_16x16x32_bf16 v[94:97], v[162:165], v[186:189], v[94:97]
	v_mfma_f32_16x16x32_bf16 v[94:97], v[158:161], v[182:185], v[94:97]
	v_mfma_f32_16x16x32_bf16 v[78:81], v[158:161], v[190:193], v[78:81]
	v_mfma_f32_16x16x32_bf16 v[78:81], v[162:165], v[210:213], v[78:81]
	v_mfma_f32_16x16x32_bf16 v[74:77], v[170:173], v[210:213], v[74:77]
	v_mfma_f32_16x16x32_bf16 v[74:77], v[166:169], v[190:193], v[74:77]
	v_mfma_f32_16x16x32_bf16 v[66:69], v[166:169], v[228:231], v[66:69]
	v_mfma_f32_16x16x32_bf16 v[66:69], v[170:173], v[232:235], v[66:69]
	v_mfma_f32_16x16x32_bf16 v[70:73], v[162:165], v[232:235], v[70:73]
	v_mfma_f32_16x16x32_bf16 v[70:73], v[158:161], v[228:231], v[70:73]
	s_setprio 0
	s_barrier
; #define PG8_STAGE(bufoff, gbase, voff) do { _Pragma("unroll") for (int _i = 0; _i < 2; ++_i) \
;         __builtin_amdgcn_global_load_lds((const unsigned*)((const char*)(gbase) + (voff)[_i]), (PG8_LAS unsigned*)(lds + (bufoff) + ldsw + _i * 8192), 16, 0, 0); } while (0)
; #define PG8_LDA(dst, b, h) do { _Pragma("unroll") for (int m = 0; m < 4; ++m) _Pragma("unroll") for (int k = 0; k < 2; ++k) dst[m][k] = *(const PG8_LAS bf16x8*)(lds + PG8_SA(b, h) + aoff + m * 2048 + k * 1024); } while (0)
; #define PG8_MMA(ai, bj, At, Bt) do { __builtin_amdgcn_s_setprio(1); _Pragma("unroll") for (int m = 0; m < 4; ++m) _Pragma("unroll") for (int n = 0; n < 2; ++n) _Pragma("unroll") for (int k = 0; k < 2; ++k) \
;         acc[ai][bj][m][n] = __builtin_amdgcn_mfma_f32_16x16x32_bf16(Bt[n][k], At[m][k], acc[ai][bj][m][n], 0, 0, 0); __builtin_amdgcn_s_setprio(0); } while (0)
; #define PG8_WAIT_V(n) asm volatile("s_waitcnt vmcnt(" #n ")" ::: "memory")
; #define PG8_WAIT_L(n) asm volatile("s_waitcnt lgkmcnt(" #n ")" ::: "memory")
; #define PG8_BAR __builtin_amdgcn_s_barrier()
; #define PG8_SCHED __builtin_amdgcn_sched_barrier(0)
; template <class Epi, class Sched, bool ALIGN_EPI = false, bool SP2 = false>
; __device__ __forceinline__ void gemm_phase(PG8_LAS unsigned char* lds, const Gemm g, const Sched& S, const Epi& E) {
;     ...
;             PG8_LDA(At, 1, 1); PG8_STAGE(PG8_SB(1, 0), b3, voffB); PG8_STAGE(PG8_SB(1, 1), b3 + hstepB, voffB); PG8_STAGE(PG8_SA(1, 0), a3, voffA);
;             PG8_WAIT_V(8); PG8_WAIT_L(0); PG8_BAR; PG8_MMA(1, 0, At, B0); PG8_MMA(1, 1, At, B1); PG8_BAR; PG8_SCHED;
;     ...
;         if constexpr (ALIGN_EPI) { if (wr == 0) PG8_BAR; }
	s_mov_b32 m0, vcc_lo
	v_lshl_add_u64 v[194:195], v[194:195], 0, s[94:95]
	ds_read_b128 v[174:177], v140 offset:49152
	ds_read_b128 v[178:181], v140 offset:50176
	ds_read_b128 v[182:185], v140 offset:51200
	ds_read_b128 v[186:189], v140 offset:52224
	ds_read_b128 v[190:193], v140 offset:53248
	ds_read_b128 v[210:213], v140 offset:54272
	ds_read_b128 v[228:231], v140 offset:55296
	ds_read_b128 v[232:235], v140 offset:56320
	global_load_lds_dwordx4 v[194:195], off
	v_lshl_add_u64 v[194:195], v[214:215], 0, s[94:95]
	s_mov_b32 m0, s86
	s_nop 0
	global_load_lds_dwordx4 v[194:195], off
	v_lshl_add_u64 v[194:195], s[42:43], 0, v[0:1]
	s_mov_b32 m0, s33
	s_nop 0
	global_load_lds_dwordx4 v[194:195], off
	v_lshl_add_u64 v[194:195], s[42:43], 0, v[132:133]
	s_mov_b32 m0, s68
	s_nop 0
	global_load_lds_dwordx4 v[194:195], off
	v_lshl_add_u64 v[194:195], v[222:223], 0, s[94:95]
	s_mov_b32 m0, s77
	s_nop 0
	global_load_lds_dwordx4 v[194:195], off
	v_lshl_add_u64 v[194:195], v[224:225], 0, s[94:95]
	s_mov_b32 m0, s83
	s_nop 0
	global_load_lds_dwordx4 v[194:195], off
	s_waitcnt vmcnt(8)
	s_waitcnt lgkmcnt(0)
	s_barrier
	s_setprio 1
	s_waitcnt lgkmcnt(0)
	v_mfma_f32_16x16x32_bf16 v[62:65], v[142:145], v[174:177], v[62:65]
	v_mfma_f32_16x16x32_bf16 v[62:65], v[146:149], v[178:181], v[62:65]
	v_mfma_f32_16x16x32_bf16 v[58:61], v[154:157], v[178:181], v[58:61]
	v_mfma_f32_16x16x32_bf16 v[58:61], v[150:153], v[174:177], v[58:61]
	v_mfma_f32_16x16x32_bf16 v[50:53], v[150:153], v[182:185], v[50:53]
	v_mfma_f32_16x16x32_bf16 v[50:53], v[154:157], v[186:189], v[50:53]
	v_mfma_f32_16x16x32_bf16 v[54:57], v[146:149], v[186:189], v[54:57]
	v_mfma_f32_16x16x32_bf16 v[54:57], v[142:145], v[182:185], v[54:57]
	v_mfma_f32_16x16x32_bf16 v[38:41], v[142:145], v[190:193], v[38:41]
	v_mfma_f32_16x16x32_bf16 v[38:41], v[146:149], v[210:213], v[38:41]
	v_mfma_f32_16x16x32_bf16 v[34:37], v[154:157], v[210:213], v[34:37]
	v_mfma_f32_16x16x32_bf16 v[34:37], v[150:153], v[190:193], v[34:37]
	v_mfma_f32_16x16x32_bf16 v[18:21], v[150:153], v[228:231], v[18:21]
	v_mfma_f32_16x16x32_bf16 v[18:21], v[154:157], v[232:235], v[18:21]
	v_mfma_f32_16x16x32_bf16 v[22:25], v[146:149], v[232:235], v[22:25]
	v_mfma_f32_16x16x32_bf16 v[22:25], v[142:145], v[228:231], v[22:25]
	s_setprio 0
	s_setprio 1
	v_mfma_f32_16x16x32_bf16 v[46:49], v[158:161], v[174:177], v[46:49]
	v_mfma_f32_16x16x32_bf16 v[46:49], v[162:165], v[178:181], v[46:49]
	v_mfma_f32_16x16x32_bf16 v[42:45], v[170:173], v[178:181], v[42:45]
	v_mfma_f32_16x16x32_bf16 v[42:45], v[166:169], v[174:177], v[42:45]
	v_mfma_f32_16x16x32_bf16 v[26:29], v[166:169], v[182:185], v[26:29]
	v_mfma_f32_16x16x32_bf16 v[26:29], v[170:173], v[186:189], v[26:29]
	v_mfma_f32_16x16x32_bf16 v[30:33], v[162:165], v[186:189], v[30:33]
	v_mfma_f32_16x16x32_bf16 v[30:33], v[158:161], v[182:185], v[30:33]
	v_mfma_f32_16x16x32_bf16 v[14:17], v[158:161], v[190:193], v[14:17]
	v_mfma_f32_16x16x32_bf16 v[14:17], v[162:165], v[210:213], v[14:17]
	v_mfma_f32_16x16x32_bf16 v[10:13], v[170:173], v[210:213], v[10:13]
	v_mfma_f32_16x16x32_bf16 v[10:13], v[166:169], v[190:193], v[10:13]
	v_mfma_f32_16x16x32_bf16 v[2:5], v[166:169], v[228:231], v[2:5]
	v_mfma_f32_16x16x32_bf16 v[2:5], v[170:173], v[232:235], v[2:5]
	v_mfma_f32_16x16x32_bf16 v[6:9], v[162:165], v[232:235], v[6:9]
	v_mfma_f32_16x16x32_bf16 v[6:9], v[158:161], v[228:231], v[6:9]
	s_setprio 0
	s_barrier
	s_movk_i32 s44, 0x100
	s_andn2_b64 vcc, exec, s[6:7]
	s_mov_b64 s[42:43], -1
	s_mov_b64 s[6:7], 0
	s_cbranch_vccz .LBB0_1403
	s_and_b64 vcc, exec, s[12:13]
	s_mov_b32 s91, 0x6c000
	s_cbranch_vccz .LBB0_1406
	s_barrier

; #define PG8_STAGE(bufoff, gbase, voff) do { _Pragma("unroll") for (int _i = 0; _i < 2; ++_i) \
;         __builtin_amdgcn_global_load_lds((const unsigned*)((const char*)(gbase) + (voff)[_i]), (PG8_LAS unsigned*)(lds + (bufoff) + ldsw + _i * 8192), 16, 0, 0); } while (0)
; #define PG8_LDA(dst, b, h) do { _Pragma("unroll") for (int m = 0; m < 4; ++m) _Pragma("unroll") for (int k = 0; k < 2; ++k) dst[m][k] = *(const PG8_LAS bf16x8*)(lds + PG8_SA(b, h) + aoff + m * 2048 + k * 1024); } while (0)
; #define PG8_LDB(dst, b, h) do { _Pragma("unroll") for (int n = 0; n < 2; ++n) _Pragma("unroll") for (int k = 0; k < 2; ++k) dst[n][k] = *(const PG8_LAS bf16x8*)(lds + PG8_SB(b, h) + boff + n * 2048 + k * 1024); } while (0)
; #define PG8_MMA(ai, bj, At, Bt) do { __builtin_amdgcn_s_setprio(1); _Pragma("unroll") for (int m = 0; m < 4; ++m) _Pragma("unroll") for (int n = 0; n < 2; ++n) _Pragma("unroll") for (int k = 0; k < 2; ++k) \
;         acc[ai][bj][m][n] = __builtin_amdgcn_mfma_f32_16x16x32_bf16(Bt[n][k], At[m][k], acc[ai][bj][m][n], 0, 0, 0); __builtin_amdgcn_s_setprio(0); } while (0)
; #define PG8_WAIT_V(n) asm volatile("s_waitcnt vmcnt(" #n ")" ::: "memory")
; #define PG8_WAIT_L(n) asm volatile("s_waitcnt lgkmcnt(" #n ")" ::: "memory")
; template <class Epi, class Sched, bool ALIGN_EPI = false, bool SP2 = false>
; __device__ __forceinline__ void gemm_phase(PG8_LAS unsigned char* lds, const Gemm g, const Sched& S, const Epi& E) {
;     ...
;             const bool last = (t == nt - 2);
;             const char* a1 = cA + (size_t)(t + 1) * kstep;
;             const char* a2 = last ? nA : cA + (size_t)(t + 2) * kstep; const char* b2 = last ? nB : cB + (size_t)(t + 2) * kstep;
;             const char* a3 = a2 + kstep; const char* b3 = b2 + kstep;
;             if (last && has_next) S.a_ready(nxt);
;             if constexpr (SP2) {
;             PG8_LDB(B0, 0, 0); PG8_LDB(B1, 0, 1); PG8_SCHED; PG8_LDA(At, 0, 0); PG8_STAGE(PG8_SA(1, 1), a1 + hstepA, voffA);
;             PG8_WAIT_V(8); PG8_WAIT_L(0); PG8_BAR; PG8_MMA(0, 0, At, B0); PG8_MMA(0, 1, At, B1); PG8_BAR; PG8_SCHED;
;             PG8_LDA(At, 0, 1); PG8_STAGE(PG8_SB(0, 0), b2, voffB); PG8_STAGE(PG8_SB(0, 1), b2 + hstepB, voffB); PG8_STAGE(PG8_SA(0, 0), a2, voffA);
;             PG8_WAIT_V(8); PG8_WAIT_L(0); PG8_BAR; PG8_MMA(1, 0, At, B0); PG8_MMA(1, 1, At, B1); PG8_BAR; PG8_SCHED;
.LBB0_1434:
	s_add_u32 s2, s6, 0xfff80080
	s_addc_u32 s33, s7, -1
	s_add_i32 s63, s17, 0x100
	s_cmp_eq_u32 s62, 28
	s_cselect_b32 s45, s35, s33
	s_cselect_b32 s44, s58, s2
	v_add_u32_e32 v146, s63, v149
	s_cselect_b32 s43, s27, s61
	s_cselect_b32 s42, s59, s60
	s_add_i32 s2, s24, 0x100
	ds_read_b128 v[142:145], v146
	ds_read_b128 v[154:157], v146 offset:1024
	ds_read_b128 v[158:161], v146 offset:2048
	ds_read_b128 v[162:165], v146 offset:3072
	v_add_u32_e32 v146, s2, v149
	ds_read_b128 v[166:169], v146
	ds_read_b128 v[170:173], v146 offset:1024
	ds_read_b128 v[174:177], v146 offset:2048
	ds_read_b128 v[178:181], v146 offset:3072
	v_lshl_add_u64 v[146:147], s[6:7], 0, v[138:139]
	s_add_i32 m0, s46, 0xc000
	ds_read_b128 v[182:185], v152
	ds_read_b128 v[186:189], v152 offset:1024
	ds_read_b128 v[190:193], v152 offset:2048
	ds_read_b128 v[210:213], v152 offset:3072
	ds_read_b128 v[228:231], v152 offset:4096
	ds_read_b128 v[232:235], v152 offset:5120
	ds_read_b128 v[236:239], v152 offset:6144
	ds_read_b128 v[240:243], v152 offset:7168
	global_load_lds_dwordx4 v[146:147], off
	v_lshl_add_u64 v[146:147], s[6:7], 0, v[140:141]
	s_add_i32 m0, s46, 0xe000
	s_nop 0
	global_load_lds_dwordx4 v[146:147], off
	s_waitcnt vmcnt(8)
	s_waitcnt lgkmcnt(0)
	s_barrier
	s_setprio 1
	s_waitcnt lgkmcnt(0)
	v_mfma_f32_16x16x32_bf16 v[126:129], v[142:145], v[182:185], v[126:129]
	v_mfma_f32_16x16x32_bf16 v[126:129], v[154:157], v[186:189], v[126:129]
	v_mfma_f32_16x16x32_bf16 v[122:125], v[162:165], v[186:189], v[122:125]
	v_mfma_f32_16x16x32_bf16 v[122:125], v[158:161], v[182:185], v[122:125]
	v_mfma_f32_16x16x32_bf16 v[106:109], v[158:161], v[190:193], v[106:109]
	v_mfma_f32_16x16x32_bf16 v[106:109], v[162:165], v[210:213], v[106:109]
	v_mfma_f32_16x16x32_bf16 v[110:113], v[154:157], v[210:213], v[110:113]
	v_mfma_f32_16x16x32_bf16 v[110:113], v[142:145], v[190:193], v[110:113]
	v_mfma_f32_16x16x32_bf16 v[94:97], v[142:145], v[228:231], v[94:97]
	v_mfma_f32_16x16x32_bf16 v[94:97], v[154:157], v[232:235], v[94:97]
	v_mfma_f32_16x16x32_bf16 v[90:93], v[162:165], v[232:235], v[90:93]
	v_mfma_f32_16x16x32_bf16 v[90:93], v[158:161], v[228:231], v[90:93]
	v_mfma_f32_16x16x32_bf16 v[74:77], v[158:161], v[236:239], v[74:77]
	v_mfma_f32_16x16x32_bf16 v[74:77], v[162:165], v[240:243], v[74:77]
	v_mfma_f32_16x16x32_bf16 v[78:81], v[154:157], v[240:243], v[78:81]
	v_mfma_f32_16x16x32_bf16 v[78:81], v[142:145], v[236:239], v[78:81]
	s_setprio 0
	s_cmp_eq_u32 s53, 18
	s_cbranch_scc1 .Linp_skip_0
	s_setprio 1
	v_mfma_f32_16x16x32_bf16 v[118:121], v[166:169], v[182:185], v[118:121]
	v_mfma_f32_16x16x32_bf16 v[118:121], v[170:173], v[186:189], v[118:121]
	v_mfma_f32_16x16x32_bf16 v[114:117], v[178:181], v[186:189], v[114:117]
	v_mfma_f32_16x16x32_bf16 v[114:117], v[174:177], v[182:185], v[114:117]
	v_mfma_f32_16x16x32_bf16 v[98:101], v[174:177], v[190:193], v[98:101]
	v_mfma_f32_16x16x32_bf16 v[98:101], v[178:181], v[210:213], v[98:101]
	v_mfma_f32_16x16x32_bf16 v[102:105], v[170:173], v[210:213], v[102:105]
	v_mfma_f32_16x16x32_bf16 v[102:105], v[166:169], v[190:193], v[102:105]
	v_mfma_f32_16x16x32_bf16 v[86:89], v[166:169], v[228:231], v[86:89]
	v_mfma_f32_16x16x32_bf16 v[86:89], v[170:173], v[232:235], v[86:89]
	v_mfma_f32_16x16x32_bf16 v[82:85], v[178:181], v[232:235], v[82:85]
	v_mfma_f32_16x16x32_bf16 v[82:85], v[174:177], v[228:231], v[82:85]
	v_mfma_f32_16x16x32_bf16 v[66:69], v[174:177], v[236:239], v[66:69]
	v_mfma_f32_16x16x32_bf16 v[66:69], v[178:181], v[240:243], v[66:69]
	v_mfma_f32_16x16x32_bf16 v[70:73], v[170:173], v[240:243], v[70:73]
	v_mfma_f32_16x16x32_bf16 v[70:73], v[166:169], v[236:239], v[70:73]
	s_setprio 0
.Linp_skip_0:
	s_barrier
	s_add_i32 s33, s63, s36
	v_lshl_add_u64 v[146:147], s[42:43], 0, v[0:1]
	s_mov_b32 m0, s33
	ds_read_b128 v[182:185], v152 offset:16384
	ds_read_b128 v[186:189], v152 offset:17408
	ds_read_b128 v[190:193], v152 offset:18432
	ds_read_b128 v[210:213], v152 offset:19456
	ds_read_b128 v[228:231], v152 offset:20480
	ds_read_b128 v[232:235], v152 offset:21504
	ds_read_b128 v[236:239], v152 offset:22528
	ds_read_b128 v[240:243], v152 offset:23552
	global_load_lds_dwordx4 v[146:147], off
	s_add_i32 m0, s33, 0x2000
	s_add_u32 s72, s42, 0x80000
	v_lshl_add_u64 v[194:195], s[42:43], 0, v[132:133]
	s_addc_u32 s73, s43, 0
	s_add_i32 s2, s2, s36
	global_load_lds_dwordx4 v[194:195], off
	v_lshl_add_u64 v[214:215], s[72:73], 0, v[0:1]
	s_mov_b32 m0, s2
	v_lshl_add_u64 v[222:223], s[44:45], 0, v[134:135]
	global_load_lds_dwordx4 v[214:215], off
	v_lshl_add_u64 v[214:215], s[72:73], 0, v[132:133]
	s_add_i32 m0, s2, 0x2000
	s_nop 0
	global_load_lds_dwordx4 v[214:215], off
	v_lshl_add_u64 v[214:215], s[44:45], 0, v[136:137]
	s_mov_b32 m0, s46
	s_nop 0
	global_load_lds_dwordx4 v[214:215], off
	s_mov_b32 m0, s47
	s_nop 0
	global_load_lds_dwordx4 v[222:223], off
	s_waitcnt vmcnt(8)
	s_waitcnt lgkmcnt(0)
	s_barrier
	s_setprio 1
	s_waitcnt lgkmcnt(0)
	v_mfma_f32_16x16x32_bf16 v[62:65], v[142:145], v[182:185], v[62:65]
	v_mfma_f32_16x16x32_bf16 v[62:65], v[154:157], v[186:189], v[62:65]
	v_mfma_f32_16x16x32_bf16 v[58:61], v[162:165], v[186:189], v[58:61]
	v_mfma_f32_16x16x32_bf16 v[58:61], v[158:161], v[182:185], v[58:61]
	v_mfma_f32_16x16x32_bf16 v[42:45], v[158:161], v[190:193], v[42:45]
	v_mfma_f32_16x16x32_bf16 v[42:45], v[162:165], v[210:213], v[42:45]
	v_mfma_f32_16x16x32_bf16 v[46:49], v[154:157], v[210:213], v[46:49]
	v_mfma_f32_16x16x32_bf16 v[46:49], v[142:145], v[190:193], v[46:49]
	v_mfma_f32_16x16x32_bf16 v[30:33], v[142:145], v[228:231], v[30:33]
	v_mfma_f32_16x16x32_bf16 v[30:33], v[154:157], v[232:235], v[30:33]
	v_mfma_f32_16x16x32_bf16 v[26:29], v[162:165], v[232:235], v[26:29]
	v_mfma_f32_16x16x32_bf16 v[26:29], v[158:161], v[228:231], v[26:29]
	v_mfma_f32_16x16x32_bf16 v[10:13], v[158:161], v[236:239], v[10:13]
	v_mfma_f32_16x16x32_bf16 v[10:13], v[162:165], v[240:243], v[10:13]
	v_mfma_f32_16x16x32_bf16 v[14:17], v[154:157], v[240:243], v[14:17]
	v_mfma_f32_16x16x32_bf16 v[14:17], v[142:145], v[236:239], v[14:17]
	s_setprio 0
	s_cmp_eq_u32 s53, 18
	s_cbranch_scc1 .Linp_skip_1
; #define PG8_STAGE(bufoff, gbase, voff) do { _Pragma("unroll") for (int _i = 0; _i < 2; ++_i) \
;         __builtin_amdgcn_global_load_lds((const unsigned*)((const char*)(gbase) + (voff)[_i]), (PG8_LAS unsigned*)(lds + (bufoff) + ldsw + _i * 8192), 16, 0, 0); } while (0)
; #define PG8_LDA(dst, b, h) do { _Pragma("unroll") for (int m = 0; m < 4; ++m) _Pragma("unroll") for (int k = 0; k < 2; ++k) dst[m][k] = *(const PG8_LAS bf16x8*)(lds + PG8_SA(b, h) + aoff + m * 2048 + k * 1024); } while (0)
; #define PG8_LDB(dst, b, h) do { _Pragma("unroll") for (int n = 0; n < 2; ++n) _Pragma("unroll") for (int k = 0; k < 2; ++k) dst[n][k] = *(const PG8_LAS bf16x8*)(lds + PG8_SB(b, h) + boff + n * 2048 + k * 1024); } while (0)
; #define PG8_MMA(ai, bj, At, Bt) do { __builtin_amdgcn_s_setprio(1); _Pragma("unroll") for (int m = 0; m < 4; ++m) _Pragma("unroll") for (int n = 0; n < 2; ++n) _Pragma("unroll") for (int k = 0; k < 2; ++k) \
;         acc[ai][bj][m][n] = __builtin_amdgcn_mfma_f32_16x16x32_bf16(Bt[n][k], At[m][k], acc[ai][bj][m][n], 0, 0, 0); __builtin_amdgcn_s_setprio(0); } while (0)
; #define PG8_WAIT_V(n) asm volatile("s_waitcnt vmcnt(" #n ")" ::: "memory")
; #define PG8_WAIT_L(n) asm volatile("s_waitcnt lgkmcnt(" #n ")" ::: "memory")
; #define PG8_BAR __builtin_amdgcn_s_barrier()
; #define PG8_SCHED __builtin_amdgcn_sched_barrier(0)
; template <class Epi, class Sched, bool ALIGN_EPI = false, bool SP2 = false>
; __device__ __forceinline__ void gemm_phase(PG8_LAS unsigned char* lds, const Gemm g, const Sched& S, const Epi& E) {
;     ...
;             PG8_WAIT_V(8); PG8_WAIT_L(0); PG8_BAR; PG8_MMA(1, 0, At, B0); PG8_MMA(1, 1, At, B1); PG8_BAR; PG8_SCHED;
;             PG8_LDB(B0, 1, 0); PG8_LDB(B1, 1, 1); PG8_SCHED; PG8_LDA(At, 1, 0); PG8_STAGE(PG8_SA(0, 1), a2 + hstepA, voffA);
;             PG8_WAIT_V(8); PG8_WAIT_L(0); PG8_BAR; PG8_MMA(0, 0, At, B0); PG8_MMA(0, 1, At, B1); PG8_BAR; PG8_SCHED;
	s_setprio 1
	v_mfma_f32_16x16x32_bf16 v[54:57], v[166:169], v[182:185], v[54:57]
	v_mfma_f32_16x16x32_bf16 v[54:57], v[170:173], v[186:189], v[54:57]
	v_mfma_f32_16x16x32_bf16 v[50:53], v[178:181], v[186:189], v[50:53]
	v_mfma_f32_16x16x32_bf16 v[50:53], v[174:177], v[182:185], v[50:53]
	v_mfma_f32_16x16x32_bf16 v[34:37], v[174:177], v[190:193], v[34:37]
	v_mfma_f32_16x16x32_bf16 v[34:37], v[178:181], v[210:213], v[34:37]
	v_mfma_f32_16x16x32_bf16 v[38:41], v[170:173], v[210:213], v[38:41]
	v_mfma_f32_16x16x32_bf16 v[38:41], v[166:169], v[190:193], v[38:41]
	v_mfma_f32_16x16x32_bf16 v[22:25], v[166:169], v[228:231], v[22:25]
	v_mfma_f32_16x16x32_bf16 v[22:25], v[170:173], v[232:235], v[22:25]
	v_mfma_f32_16x16x32_bf16 v[18:21], v[178:181], v[232:235], v[18:21]
	v_mfma_f32_16x16x32_bf16 v[18:21], v[174:177], v[228:231], v[18:21]
	v_mfma_f32_16x16x32_bf16 v[2:5], v[174:177], v[236:239], v[2:5]
	v_mfma_f32_16x16x32_bf16 v[2:5], v[178:181], v[240:243], v[2:5]
	v_mfma_f32_16x16x32_bf16 v[6:9], v[170:173], v[240:243], v[6:9]
	v_mfma_f32_16x16x32_bf16 v[6:9], v[166:169], v[236:239], v[6:9]
	s_setprio 0
.Linp_skip_1:
	s_barrier
	s_add_i32 s2, s87, 0x100
	v_add_u32_e32 v148, s2, v149
	s_add_i32 s33, s69, 0x100
	ds_read_b128 v[142:145], v148
	ds_read_b128 v[154:157], v148 offset:1024
	ds_read_b128 v[158:161], v148 offset:2048
	ds_read_b128 v[162:165], v148 offset:3072
	v_add_u32_e32 v148, s33, v149
	ds_read_b128 v[166:169], v148
	ds_read_b128 v[170:173], v148 offset:1024
	ds_read_b128 v[174:177], v148 offset:2048
	ds_read_b128 v[178:181], v148 offset:3072
	s_add_u32 s44, s44, 0x80000
	s_addc_u32 s45, s45, 0
	s_mov_b32 m0, s48
	v_lshl_add_u64 v[224:225], s[44:45], 0, v[136:137]
	ds_read_b128 v[182:185], v152 offset:32768
	ds_read_b128 v[186:189], v152 offset:33792
	ds_read_b128 v[190:193], v152 offset:34816
	ds_read_b128 v[210:213], v152 offset:35840
	ds_read_b128 v[228:231], v152 offset:36864
	ds_read_b128 v[232:235], v152 offset:37888
	ds_read_b128 v[236:239], v152 offset:38912
	ds_read_b128 v[240:243], v152 offset:39936
	global_load_lds_dwordx4 v[224:225], off
	v_lshl_add_u64 v[224:225], s[44:45], 0, v[134:135]
	s_mov_b32 m0, s49
	s_nop 0
	global_load_lds_dwordx4 v[224:225], off
	s_waitcnt vmcnt(8)
	s_waitcnt lgkmcnt(0)
	s_barrier
	s_setprio 1
	s_waitcnt lgkmcnt(0)
	v_mfma_f32_16x16x32_bf16 v[126:129], v[142:145], v[182:185], v[126:129]
	v_mfma_f32_16x16x32_bf16 v[126:129], v[154:157], v[186:189], v[126:129]
	v_mfma_f32_16x16x32_bf16 v[122:125], v[162:165], v[186:189], v[122:125]
	v_mfma_f32_16x16x32_bf16 v[122:125], v[158:161], v[182:185], v[122:125]
	v_mfma_f32_16x16x32_bf16 v[106:109], v[158:161], v[190:193], v[106:109]
	v_mfma_f32_16x16x32_bf16 v[106:109], v[162:165], v[210:213], v[106:109]
	v_mfma_f32_16x16x32_bf16 v[110:113], v[154:157], v[210:213], v[110:113]
	v_mfma_f32_16x16x32_bf16 v[110:113], v[142:145], v[190:193], v[110:113]
	v_mfma_f32_16x16x32_bf16 v[94:97], v[142:145], v[228:231], v[94:97]
	v_mfma_f32_16x16x32_bf16 v[94:97], v[154:157], v[232:235], v[94:97]
	v_mfma_f32_16x16x32_bf16 v[90:93], v[162:165], v[232:235], v[90:93]
	v_mfma_f32_16x16x32_bf16 v[90:93], v[158:161], v[228:231], v[90:93]
	v_mfma_f32_16x16x32_bf16 v[74:77], v[158:161], v[236:239], v[74:77]
	v_mfma_f32_16x16x32_bf16 v[74:77], v[162:165], v[240:243], v[74:77]
	v_mfma_f32_16x16x32_bf16 v[78:81], v[154:157], v[240:243], v[78:81]
	v_mfma_f32_16x16x32_bf16 v[78:81], v[142:145], v[236:239], v[78:81]
	s_setprio 0
	s_cmp_eq_u32 s53, 18
	s_cbranch_scc1 .Linp_skip_2
	s_setprio 1
	v_mfma_f32_16x16x32_bf16 v[118:121], v[166:169], v[182:185], v[118:121]
	v_mfma_f32_16x16x32_bf16 v[118:121], v[170:173], v[186:189], v[118:121]
	v_mfma_f32_16x16x32_bf16 v[114:117], v[178:181], v[186:189], v[114:117]
	v_mfma_f32_16x16x32_bf16 v[114:117], v[174:177], v[182:185], v[114:117]
	v_mfma_f32_16x16x32_bf16 v[98:101], v[174:177], v[190:193], v[98:101]
	v_mfma_f32_16x16x32_bf16 v[98:101], v[178:181], v[210:213], v[98:101]
	v_mfma_f32_16x16x32_bf16 v[102:105], v[170:173], v[210:213], v[102:105]
	v_mfma_f32_16x16x32_bf16 v[102:105], v[166:169], v[190:193], v[102:105]
	v_mfma_f32_16x16x32_bf16 v[86:89], v[166:169], v[228:231], v[86:89]
	v_mfma_f32_16x16x32_bf16 v[86:89], v[170:173], v[232:235], v[86:89]
	v_mfma_f32_16x16x32_bf16 v[82:85], v[178:181], v[232:235], v[82:85]
	v_mfma_f32_16x16x32_bf16 v[82:85], v[174:177], v[228:231], v[82:85]
	v_mfma_f32_16x16x32_bf16 v[66:69], v[174:177], v[236:239], v[66:69]
	v_mfma_f32_16x16x32_bf16 v[66:69], v[178:181], v[240:243], v[66:69]
	v_mfma_f32_16x16x32_bf16 v[70:73], v[170:173], v[240:243], v[70:73]
	v_mfma_f32_16x16x32_bf16 v[70:73], v[166:169], v[236:239], v[70:73]
	s_setprio 0
; #define PG8_STAGE(bufoff, gbase, voff) do { _Pragma("unroll") for (int _i = 0; _i < 2; ++_i) \
;         __builtin_amdgcn_global_load_lds((const unsigned*)((const char*)(gbase) + (voff)[_i]), (PG8_LAS unsigned*)(lds + (bufoff) + ldsw + _i * 8192), 16, 0, 0); } while (0)
; #define PG8_LDA(dst, b, h) do { _Pragma("unroll") for (int m = 0; m < 4; ++m) _Pragma("unroll") for (int k = 0; k < 2; ++k) dst[m][k] = *(const PG8_LAS bf16x8*)(lds + PG8_SA(b, h) + aoff + m * 2048 + k * 1024); } while (0)
; #define PG8_MMA(ai, bj, At, Bt) do { __builtin_amdgcn_s_setprio(1); _Pragma("unroll") for (int m = 0; m < 4; ++m) _Pragma("unroll") for (int n = 0; n < 2; ++n) _Pragma("unroll") for (int k = 0; k < 2; ++k) \
;         acc[ai][bj][m][n] = __builtin_amdgcn_mfma_f32_16x16x32_bf16(Bt[n][k], At[m][k], acc[ai][bj][m][n], 0, 0, 0); __builtin_amdgcn_s_setprio(0); } while (0)
; #define PG8_WAIT_V(n) asm volatile("s_waitcnt vmcnt(" #n ")" ::: "memory")
; #define PG8_WAIT_L(n) asm volatile("s_waitcnt lgkmcnt(" #n ")" ::: "memory")
; #define PG8_BAR __builtin_amdgcn_s_barrier()
; #define PG8_SCHED __builtin_amdgcn_sched_barrier(0)
; template <class Epi, class Sched, bool ALIGN_EPI = false, bool SP2 = false>
; __device__ __forceinline__ void gemm_phase(PG8_LAS unsigned char* lds, const Gemm g, const Sched& S, const Epi& E) {
;     ...
;             PG8_LDA(At, 1, 1); PG8_STAGE(PG8_SB(1, 0), b3, voffB); PG8_STAGE(PG8_SB(1, 1), b3 + hstepB, voffB); PG8_STAGE(PG8_SA(1, 0), a3, voffA);
;             PG8_WAIT_V(8); PG8_WAIT_L(0); PG8_BAR; PG8_MMA(1, 0, At, B0); PG8_MMA(1, 1, At, B1); PG8_BAR; PG8_SCHED;
.Linp_skip_2:
	s_barrier
	s_add_i32 s2, s2, s36
	v_lshl_add_u64 v[146:147], v[146:147], 0, s[94:95]
	s_mov_b32 m0, s2
	ds_read_b128 v[182:185], v152 offset:49152
	ds_read_b128 v[186:189], v152 offset:50176
	ds_read_b128 v[190:193], v152 offset:51200
	ds_read_b128 v[210:213], v152 offset:52224
	ds_read_b128 v[228:231], v152 offset:53248
	ds_read_b128 v[232:235], v152 offset:54272
	ds_read_b128 v[236:239], v152 offset:55296
	ds_read_b128 v[240:243], v152 offset:56320
	global_load_lds_dwordx4 v[146:147], off
	s_add_i32 m0, s2, 0x2000
	s_add_u32 s42, s42, 0x80080
	v_lshl_add_u64 v[146:147], v[194:195], 0, s[94:95]
	s_addc_u32 s43, s43, 0
	s_add_i32 s2, s33, s36
	global_load_lds_dwordx4 v[146:147], off
	v_lshl_add_u64 v[146:147], s[42:43], 0, v[0:1]
	s_mov_b32 m0, s2
	s_nop 0
	global_load_lds_dwordx4 v[146:147], off
	v_lshl_add_u64 v[146:147], s[42:43], 0, v[132:133]
	s_add_i32 m0, s2, 0x2000
	s_nop 0
	global_load_lds_dwordx4 v[146:147], off
	v_lshl_add_u64 v[146:147], v[214:215], 0, s[94:95]
	s_mov_b32 m0, s50
	s_nop 0
	global_load_lds_dwordx4 v[146:147], off
	v_lshl_add_u64 v[146:147], v[222:223], 0, s[94:95]
	s_mov_b32 m0, s51
	s_nop 0
	global_load_lds_dwordx4 v[146:147], off
	s_waitcnt vmcnt(8)
	s_waitcnt lgkmcnt(0)
	s_barrier
	s_setprio 1
	s_waitcnt lgkmcnt(0)
	v_mfma_f32_16x16x32_bf16 v[62:65], v[142:145], v[182:185], v[62:65]
	v_mfma_f32_16x16x32_bf16 v[62:65], v[154:157], v[186:189], v[62:65]
	v_mfma_f32_16x16x32_bf16 v[58:61], v[162:165], v[186:189], v[58:61]
	v_mfma_f32_16x16x32_bf16 v[58:61], v[158:161], v[182:185], v[58:61]
	v_mfma_f32_16x16x32_bf16 v[42:45], v[158:161], v[190:193], v[42:45]
	v_mfma_f32_16x16x32_bf16 v[42:45], v[162:165], v[210:213], v[42:45]
	v_mfma_f32_16x16x32_bf16 v[46:49], v[154:157], v[210:213], v[46:49]
	v_mfma_f32_16x16x32_bf16 v[46:49], v[142:145], v[190:193], v[46:49]
	v_mfma_f32_16x16x32_bf16 v[30:33], v[142:145], v[228:231], v[30:33]
	v_mfma_f32_16x16x32_bf16 v[30:33], v[154:157], v[232:235], v[30:33]
	v_mfma_f32_16x16x32_bf16 v[26:29], v[162:165], v[232:235], v[26:29]
	v_mfma_f32_16x16x32_bf16 v[26:29], v[158:161], v[228:231], v[26:29]
	v_mfma_f32_16x16x32_bf16 v[10:13], v[158:161], v[236:239], v[10:13]
	v_mfma_f32_16x16x32_bf16 v[10:13], v[162:165], v[240:243], v[10:13]
	v_mfma_f32_16x16x32_bf16 v[14:17], v[154:157], v[240:243], v[14:17]
	v_mfma_f32_16x16x32_bf16 v[14:17], v[142:145], v[236:239], v[14:17]
	s_setprio 0
	s_cmp_eq_u32 s53, 18
	s_cbranch_scc1 .Linp_skip_3
	s_setprio 1
	v_mfma_f32_16x16x32_bf16 v[54:57], v[166:169], v[182:185], v[54:57]
	v_mfma_f32_16x16x32_bf16 v[54:57], v[170:173], v[186:189], v[54:57]
	v_mfma_f32_16x16x32_bf16 v[50:53], v[178:181], v[186:189], v[50:53]
	v_mfma_f32_16x16x32_bf16 v[50:53], v[174:177], v[182:185], v[50:53]
	v_mfma_f32_16x16x32_bf16 v[34:37], v[174:177], v[190:193], v[34:37]
	v_mfma_f32_16x16x32_bf16 v[34:37], v[178:181], v[210:213], v[34:37]
	v_mfma_f32_16x16x32_bf16 v[38:41], v[170:173], v[210:213], v[38:41]
	v_mfma_f32_16x16x32_bf16 v[38:41], v[166:169], v[190:193], v[38:41]
	v_mfma_f32_16x16x32_bf16 v[22:25], v[166:169], v[228:231], v[22:25]
	v_mfma_f32_16x16x32_bf16 v[22:25], v[170:173], v[232:235], v[22:25]
	v_mfma_f32_16x16x32_bf16 v[18:21], v[178:181], v[232:235], v[18:21]
	v_mfma_f32_16x16x32_bf16 v[18:21], v[174:177], v[228:231], v[18:21]
	v_mfma_f32_16x16x32_bf16 v[2:5], v[174:177], v[236:239], v[2:5]
	v_mfma_f32_16x16x32_bf16 v[2:5], v[178:181], v[240:243], v[2:5]
	v_mfma_f32_16x16x32_bf16 v[6:9], v[170:173], v[240:243], v[6:9]
	v_mfma_f32_16x16x32_bf16 v[6:9], v[166:169], v[236:239], v[6:9]
	s_setprio 0
